# speedup vs baseline: 1.0670x; 1.0096x over previous
; #define PG8_STAGE(bufoff, gbase, voff) do { _Pragma("unroll") for (int _i = 0; _i < 2; ++_i) \
;         __builtin_amdgcn_global_load_lds((const unsigned*)((const char*)(gbase) + (voff)[_i]), (PG8_LAS unsigned*)(lds + (bufoff) + ldsw + _i * 8192), 16, 0, 0); } while (0)
; #define PG8_LDA(dst, b, h) do { _Pragma("unroll") for (int m = 0; m < 4; ++m) _Pragma("unroll") for (int k = 0; k < 2; ++k) dst[m][k] = *(const PG8_LAS bf16x8*)(lds + PG8_SA(b, h) + aoff + m * 2048 + k * 1024); } while (0)
; #define PG8_WAIT_V(n) asm volatile("s_waitcnt vmcnt(" #n ")" ::: "memory")
; #define PG8_BAR __builtin_amdgcn_s_barrier()
; template <class Epi, class Sched, bool ALIGN_EPI = false, bool SP2 = false>
; __device__ __forceinline__ void gemm_phase(PG8_LAS unsigned char* lds, const Gemm g, const Sched& S, const Epi& E, const int tid) {
;     ...
;     Unit cur, nxt; int ui = 0;
;     if (!S.next(0, cur)) return;
;     f32x4 acc[2][2][4][2];
; #pragma unroll
;     for (int a = 0; a < 2; ++a)
; #pragma unroll
;         for (int b = 0; b < 2; ++b)
; #pragma unroll
;             for (int m = 0; m < 4; ++m)
; #pragma unroll
;                 for (int n = 0; n < 2; ++n) acc[a][b][m][n] = (f32x4){0.f, 0.f, 0.f, 0.f};
;     ...
;         const bool has_next = S.next(ui + 1, nxt);
;         const char* nA = has_next ? (const char*)g.A + (size_t)nxt.pm * tstep : cA; const char* nB = has_next ? (const char*)g.Bt + (size_t)nxt.pn * tstep : cB;
;         for (int t = 0; t < nt; t += 2) {
;             const bool last = (t == nt - 2);
;             const char* a1 = cA + (size_t)(t + 1) * kstep;
;             const char* a2 = last ? nA : cA + (size_t)(t + 2) * kstep; const char* b2 = last ? nB : cB + (size_t)(t + 2) * kstep;
;             const char* a3 = a2 + kstep; const char* b3 = b2 + kstep;
;             if (last && has_next) S.a_ready(nxt);
;             if constexpr (SP2) {
;             PG8_LDB(B0, 0, 0); PG8_LDB(B1, 0, 1); PG8_SCHED; PG8_LDA(At, 0, 0); PG8_STAGE(PG8_SA(1, 1), a1 + hstep, voffA);
;             PG8_WAIT_V(8); PG8_WAIT_L(0); PG8_BAR; PG8_MMA(0, 0, At, B0); PG8_MMA(0, 1, At, B1); PG8_BAR; PG8_SCHED;
;             PG8_LDA(At, 0, 1); PG8_STAGE(PG8_SB(0, 0), b2, voffB); PG8_STAGE(PG8_SB(0, 1), b2 + hstep, voffB); PG8_STAGE(PG8_SA(0, 0), a2, voffA);
;             PG8_WAIT_V(8); PG8_WAIT_L(0); PG8_BAR; PG8_MMA(1, 0, At, B0); PG8_MMA(1, 1, At, B1); PG8_BAR; PG8_SCHED;
.LBB0_59:
	s_add_u32 s26, s26, 0x80
	s_addc_u32 s27, s27, 0
	s_add_u32 s36, s30, 0x100
	s_addc_u32 s37, s31, 0
	s_mov_b32 s30, 0
	s_add_i32 s44, s30, 2
	s_add_u32 s45, s26, 0x80
	s_addc_u32 s31, s27, 0
	s_add_i32 s63, 0, 0x10000
	s_cmp_eq_u32 s58, s30
	s_cselect_b32 s31, s21, s31
	s_cselect_b32 s30, s20, s45
	s_cselect_b32 s65, s23, s37
	s_cselect_b32 s64, s22, s36
	s_add_i32 s45, 0, 0x14000
	v_add_u32_e32 v154, s63, v143
	v_add_u32_e32 v158, s45, v143
	ds_read_b128 v[138:141], v154
	ds_read_b128 v[146:149], v154 offset:1024
	ds_read_b128 v[150:153], v154 offset:2048
	ds_read_b128 v[154:157], v154 offset:3072
	ds_read_b128 v[162:165], v158
	ds_read_b128 v[166:169], v158 offset:1024
	ds_read_b128 v[170:173], v158 offset:2048
	ds_read_b128 v[184:187], v158 offset:3072
	v_lshl_add_u64 v[158:159], s[26:27], 0, v[134:135]
	s_add_i32 m0, s47, 0xc000
	ds_read_b128 v[188:191], v145
	ds_read_b128 v[192:195], v145 offset:1024
	ds_read_b128 v[208:211], v145 offset:2048
	ds_read_b128 v[214:217], v145 offset:3072
	ds_read_b128 v[218:221], v145 offset:4096
	ds_read_b128 v[222:225], v145 offset:5120
	ds_read_b128 v[226:229], v145 offset:6144
	ds_read_b128 v[230:233], v145 offset:7168
	global_load_lds_dwordx4 v[158:159], off
	v_lshl_add_u64 v[158:159], s[26:27], 0, v[136:137]
	s_add_i32 m0, s47, 0xe000
	s_nop 0
	global_load_lds_dwordx4 v[158:159], off
	s_waitcnt vmcnt(24)
	s_waitcnt lgkmcnt(0)
	s_barrier
	s_setprio 1
	s_waitcnt lgkmcnt(0)
	v_mfma_f32_16x16x32_bf16 v[124:127], v[138:141], v[188:191], 0
	v_mfma_f32_16x16x32_bf16 v[120:123], v[150:153], v[188:191], 0
	v_mfma_f32_16x16x32_bf16 v[108:111], v[138:141], v[208:211], 0
	v_mfma_f32_16x16x32_bf16 v[104:107], v[150:153], v[208:211], 0
	v_mfma_f32_16x16x32_bf16 v[92:95], v[138:141], v[218:221], 0
	v_mfma_f32_16x16x32_bf16 v[88:91], v[150:153], v[218:221], 0
	v_mfma_f32_16x16x32_bf16 v[76:79], v[138:141], v[226:229], 0
	v_mfma_f32_16x16x32_bf16 v[72:75], v[150:153], v[226:229], 0
	v_mfma_f32_16x16x32_bf16 v[124:127], v[146:149], v[192:195], v[124:127]
	v_mfma_f32_16x16x32_bf16 v[120:123], v[154:157], v[192:195], v[120:123]
	v_mfma_f32_16x16x32_bf16 v[108:111], v[146:149], v[214:217], v[108:111]
	v_mfma_f32_16x16x32_bf16 v[104:107], v[154:157], v[214:217], v[104:107]
	v_mfma_f32_16x16x32_bf16 v[92:95], v[146:149], v[222:225], v[92:95]
	v_mfma_f32_16x16x32_bf16 v[88:91], v[154:157], v[222:225], v[88:91]
	v_mfma_f32_16x16x32_bf16 v[76:79], v[146:149], v[230:233], v[76:79]
	v_mfma_f32_16x16x32_bf16 v[72:75], v[154:157], v[230:233], v[72:75]
	s_setprio 0
	s_setprio 1
	v_mfma_f32_16x16x32_bf16 v[116:119], v[162:165], v[188:191], 0
	v_mfma_f32_16x16x32_bf16 v[112:115], v[170:173], v[188:191], 0
	v_mfma_f32_16x16x32_bf16 v[100:103], v[162:165], v[208:211], 0
	v_mfma_f32_16x16x32_bf16 v[96:99], v[170:173], v[208:211], 0
	v_mfma_f32_16x16x32_bf16 v[84:87], v[162:165], v[218:221], 0
	v_mfma_f32_16x16x32_bf16 v[80:83], v[170:173], v[218:221], 0
	v_mfma_f32_16x16x32_bf16 v[68:71], v[162:165], v[226:229], 0
	v_mfma_f32_16x16x32_bf16 v[64:67], v[170:173], v[226:229], 0
	v_mfma_f32_16x16x32_bf16 v[116:119], v[166:169], v[192:195], v[116:119]
	v_mfma_f32_16x16x32_bf16 v[112:115], v[184:187], v[192:195], v[112:115]
	v_mfma_f32_16x16x32_bf16 v[100:103], v[166:169], v[214:217], v[100:103]
	v_mfma_f32_16x16x32_bf16 v[96:99], v[184:187], v[214:217], v[96:99]
	v_mfma_f32_16x16x32_bf16 v[84:87], v[166:169], v[222:225], v[84:87]
	v_mfma_f32_16x16x32_bf16 v[80:83], v[184:187], v[222:225], v[80:83]
	v_mfma_f32_16x16x32_bf16 v[68:71], v[166:169], v[230:233], v[68:71]
	v_mfma_f32_16x16x32_bf16 v[64:67], v[184:187], v[230:233], v[64:67]
	s_setprio 0
	s_barrier
	s_add_i32 s63, s63, s46
	v_lshl_add_u64 v[158:159], s[64:65], 0, v[160:161]
	s_mov_b32 m0, s63
	ds_read_b128 v[188:191], v145 offset:16384
	ds_read_b128 v[192:195], v145 offset:17408
	ds_read_b128 v[208:211], v145 offset:18432
	ds_read_b128 v[214:217], v145 offset:19456
	ds_read_b128 v[218:221], v145 offset:20480
	ds_read_b128 v[222:225], v145 offset:21504
	ds_read_b128 v[226:229], v145 offset:22528
	ds_read_b128 v[230:233], v145 offset:23552
	global_load_lds_dwordx4 v[158:159], off
	s_add_i32 m0, s63, 0x2000
	v_lshl_add_u64 v[174:175], s[64:65], 0, v[132:133]
	s_add_u32 s64, s64, s12
	s_addc_u32 s65, s65, 0
	s_add_i32 s45, s45, s46
	global_load_lds_dwordx4 v[174:175], off
	v_lshl_add_u64 v[178:179], s[64:65], 0, v[160:161]
	s_mov_b32 m0, s45
	v_lshl_add_u64 v[180:181], s[64:65], 0, v[132:133]
	global_load_lds_dwordx4 v[178:179], off
	s_add_i32 m0, s45, 0x2000
	v_lshl_add_u64 v[196:197], s[30:31], 0, v[128:129]
	global_load_lds_dwordx4 v[180:181], off
	s_mov_b32 m0, s47
	v_lshl_add_u64 v[198:199], s[30:31], 0, v[130:131]
	global_load_lds_dwordx4 v[196:197], off
	s_mov_b32 m0, s48
	s_nop 0
	global_load_lds_dwordx4 v[198:199], off
	s_cmp_lt_u32 s59, 2
	s_cbranch_scc1 .Lmy_w8_0
	s_waitcnt vmcnt(24)
	s_branch .Lmy_wj_0
.Lmy_w8_0:
	s_waitcnt vmcnt(8)
; #define PG8_STAGE(bufoff, gbase, voff) do { _Pragma("unroll") for (int _i = 0; _i < 2; ++_i) \
;         __builtin_amdgcn_global_load_lds((const unsigned*)((const char*)(gbase) + (voff)[_i]), (PG8_LAS unsigned*)(lds + (bufoff) + ldsw + _i * 8192), 16, 0, 0); } while (0)
; #define PG8_LDA(dst, b, h) do { _Pragma("unroll") for (int m = 0; m < 4; ++m) _Pragma("unroll") for (int k = 0; k < 2; ++k) dst[m][k] = *(const PG8_LAS bf16x8*)(lds + PG8_SA(b, h) + aoff + m * 2048 + k * 1024); } while (0)
; #define PG8_LDB(dst, b, h) do { _Pragma("unroll") for (int n = 0; n < 2; ++n) _Pragma("unroll") for (int k = 0; k < 2; ++k) dst[n][k] = *(const PG8_LAS bf16x8*)(lds + PG8_SB(b, h) + boff + n * 2048 + k * 1024); } while (0)
; #define PG8_MMA(ai, bj, At, Bt) do { __builtin_amdgcn_s_setprio(1); _Pragma("unroll") for (int m = 0; m < 4; ++m) _Pragma("unroll") for (int n = 0; n < 2; ++n) _Pragma("unroll") for (int k = 0; k < 2; ++k) \
;         acc[ai][bj][m][n] = __builtin_amdgcn_mfma_f32_16x16x32_bf16(Bt[n][k], At[m][k], acc[ai][bj][m][n], 0, 0, 0); __builtin_amdgcn_s_setprio(0); } while (0)
; #define PG8_WAIT_V(n) asm volatile("s_waitcnt vmcnt(" #n ")" ::: "memory")
; #define PG8_WAIT_L(n) asm volatile("s_waitcnt lgkmcnt(" #n ")" ::: "memory")
; #define PG8_BAR __builtin_amdgcn_s_barrier()
; #define PG8_SCHED __builtin_amdgcn_sched_barrier(0)
; template <class Epi, class Sched, bool ALIGN_EPI = false, bool SP2 = false>
; __device__ __forceinline__ void gemm_phase(PG8_LAS unsigned char* lds, const Gemm g, const Sched& S, const Epi& E, const int tid) {
;     ...
;             PG8_WAIT_V(8); PG8_WAIT_L(0); PG8_BAR; PG8_MMA(1, 0, At, B0); PG8_MMA(1, 1, At, B1); PG8_BAR; PG8_SCHED;
;             PG8_LDB(B0, 1, 0); PG8_LDB(B1, 1, 1); PG8_SCHED; PG8_LDA(At, 1, 0); PG8_STAGE(PG8_SA(0, 1), a2 + hstep, voffA);
;             PG8_WAIT_V(8); PG8_WAIT_L(0); PG8_BAR; PG8_MMA(0, 0, At, B0); PG8_MMA(0, 1, At, B1); PG8_BAR; PG8_SCHED;
.Lmy_wj_0:
	s_waitcnt lgkmcnt(0)
	s_barrier
	s_setprio 1
	s_waitcnt lgkmcnt(0)
	v_mfma_f32_16x16x32_bf16 v[60:63], v[138:141], v[188:191], 0
	v_mfma_f32_16x16x32_bf16 v[56:59], v[150:153], v[188:191], 0
	v_mfma_f32_16x16x32_bf16 v[44:47], v[138:141], v[208:211], 0
	v_mfma_f32_16x16x32_bf16 v[40:43], v[150:153], v[208:211], 0
	v_mfma_f32_16x16x32_bf16 v[28:31], v[138:141], v[218:221], 0
	v_mfma_f32_16x16x32_bf16 v[24:27], v[150:153], v[218:221], 0
	v_mfma_f32_16x16x32_bf16 v[12:15], v[138:141], v[226:229], 0
	v_mfma_f32_16x16x32_bf16 v[8:11], v[150:153], v[226:229], 0
	v_mfma_f32_16x16x32_bf16 v[60:63], v[146:149], v[192:195], v[60:63]
	v_mfma_f32_16x16x32_bf16 v[56:59], v[154:157], v[192:195], v[56:59]
	v_mfma_f32_16x16x32_bf16 v[44:47], v[146:149], v[214:217], v[44:47]
	v_mfma_f32_16x16x32_bf16 v[40:43], v[154:157], v[214:217], v[40:43]
	v_mfma_f32_16x16x32_bf16 v[28:31], v[146:149], v[222:225], v[28:31]
	v_mfma_f32_16x16x32_bf16 v[24:27], v[154:157], v[222:225], v[24:27]
	v_mfma_f32_16x16x32_bf16 v[12:15], v[146:149], v[230:233], v[12:15]
	v_mfma_f32_16x16x32_bf16 v[8:11], v[154:157], v[230:233], v[8:11]
	s_setprio 0
	s_setprio 1
	v_mfma_f32_16x16x32_bf16 v[52:55], v[162:165], v[188:191], 0
	v_mfma_f32_16x16x32_bf16 v[48:51], v[170:173], v[188:191], 0
	v_mfma_f32_16x16x32_bf16 v[36:39], v[162:165], v[208:211], 0
	v_mfma_f32_16x16x32_bf16 v[32:35], v[170:173], v[208:211], 0
	v_mfma_f32_16x16x32_bf16 v[20:23], v[162:165], v[218:221], 0
	v_mfma_f32_16x16x32_bf16 v[16:19], v[170:173], v[218:221], 0
	v_mfma_f32_16x16x32_bf16 v[4:7], v[162:165], v[226:229], 0
	v_mfma_f32_16x16x32_bf16 v[0:3], v[170:173], v[226:229], 0
	v_mfma_f32_16x16x32_bf16 v[52:55], v[166:169], v[192:195], v[52:55]
	v_mfma_f32_16x16x32_bf16 v[48:51], v[184:187], v[192:195], v[48:51]
	v_mfma_f32_16x16x32_bf16 v[36:39], v[166:169], v[214:217], v[36:39]
	v_mfma_f32_16x16x32_bf16 v[32:35], v[184:187], v[214:217], v[32:35]
	v_mfma_f32_16x16x32_bf16 v[20:23], v[166:169], v[222:225], v[20:23]
	v_mfma_f32_16x16x32_bf16 v[16:19], v[184:187], v[222:225], v[16:19]
	v_mfma_f32_16x16x32_bf16 v[4:7], v[166:169], v[230:233], v[4:7]
	v_mfma_f32_16x16x32_bf16 v[0:3], v[184:187], v[230:233], v[0:3]
	s_setprio 0
	s_barrier
	s_add_i32 s45, 0, 0x18000
	s_add_i32 s63, 0, 0x1c000
	v_add_u32_e32 v154, s45, v143
	v_add_u32_e32 v183, s63, v143
	ds_read_b128 v[138:141], v154
	ds_read_b128 v[146:149], v154 offset:1024
	ds_read_b128 v[150:153], v154 offset:2048
	ds_read_b128 v[154:157], v154 offset:3072
	ds_read_b128 v[162:165], v183
	ds_read_b128 v[166:169], v183 offset:1024
	ds_read_b128 v[170:173], v183 offset:2048
	ds_read_b128 v[184:187], v183 offset:3072
	s_add_u32 s30, s30, s12
	s_addc_u32 s31, s31, 0
	s_mov_b32 m0, s49
	v_lshl_add_u64 v[204:205], s[30:31], 0, v[128:129]
	ds_read_b128 v[188:191], v145 offset:32768
	ds_read_b128 v[192:195], v145 offset:33792
	ds_read_b128 v[208:211], v145 offset:34816
	ds_read_b128 v[214:217], v145 offset:35840
	ds_read_b128 v[218:221], v145 offset:36864
	ds_read_b128 v[222:225], v145 offset:37888
	ds_read_b128 v[226:229], v145 offset:38912
	ds_read_b128 v[230:233], v145 offset:39936
	global_load_lds_dwordx4 v[204:205], off
	v_lshl_add_u64 v[204:205], s[30:31], 0, v[130:131]
	s_mov_b32 m0, s50
	s_nop 0
	global_load_lds_dwordx4 v[204:205], off
	s_waitcnt vmcnt(8)
	s_waitcnt lgkmcnt(0)
	s_barrier
	s_setprio 1
	s_waitcnt lgkmcnt(0)
	v_mfma_f32_16x16x32_bf16 v[124:127], v[138:141], v[188:191], v[124:127]
	v_mfma_f32_16x16x32_bf16 v[120:123], v[150:153], v[188:191], v[120:123]
	v_mfma_f32_16x16x32_bf16 v[108:111], v[138:141], v[208:211], v[108:111]
	v_mfma_f32_16x16x32_bf16 v[104:107], v[150:153], v[208:211], v[104:107]
	v_mfma_f32_16x16x32_bf16 v[92:95], v[138:141], v[218:221], v[92:95]
	v_mfma_f32_16x16x32_bf16 v[88:91], v[150:153], v[218:221], v[88:91]
	v_mfma_f32_16x16x32_bf16 v[76:79], v[138:141], v[226:229], v[76:79]
	v_mfma_f32_16x16x32_bf16 v[72:75], v[150:153], v[226:229], v[72:75]
	v_mfma_f32_16x16x32_bf16 v[124:127], v[146:149], v[192:195], v[124:127]
	v_mfma_f32_16x16x32_bf16 v[120:123], v[154:157], v[192:195], v[120:123]
	v_mfma_f32_16x16x32_bf16 v[108:111], v[146:149], v[214:217], v[108:111]
	v_mfma_f32_16x16x32_bf16 v[104:107], v[154:157], v[214:217], v[104:107]
	v_mfma_f32_16x16x32_bf16 v[92:95], v[146:149], v[222:225], v[92:95]
	v_mfma_f32_16x16x32_bf16 v[88:91], v[154:157], v[222:225], v[88:91]
	v_mfma_f32_16x16x32_bf16 v[76:79], v[146:149], v[230:233], v[76:79]
	v_mfma_f32_16x16x32_bf16 v[72:75], v[154:157], v[230:233], v[72:75]
	s_setprio 0
	s_setprio 1
	v_mfma_f32_16x16x32_bf16 v[116:119], v[162:165], v[188:191], v[116:119]
	v_mfma_f32_16x16x32_bf16 v[112:115], v[170:173], v[188:191], v[112:115]
	v_mfma_f32_16x16x32_bf16 v[100:103], v[162:165], v[208:211], v[100:103]
	v_mfma_f32_16x16x32_bf16 v[96:99], v[170:173], v[208:211], v[96:99]
	v_mfma_f32_16x16x32_bf16 v[84:87], v[162:165], v[218:221], v[84:87]
	v_mfma_f32_16x16x32_bf16 v[80:83], v[170:173], v[218:221], v[80:83]
	v_mfma_f32_16x16x32_bf16 v[68:71], v[162:165], v[226:229], v[68:71]
	v_mfma_f32_16x16x32_bf16 v[64:67], v[170:173], v[226:229], v[64:67]
	v_mfma_f32_16x16x32_bf16 v[116:119], v[166:169], v[192:195], v[116:119]
	v_mfma_f32_16x16x32_bf16 v[112:115], v[184:187], v[192:195], v[112:115]
	v_mfma_f32_16x16x32_bf16 v[100:103], v[166:169], v[214:217], v[100:103]
	v_mfma_f32_16x16x32_bf16 v[96:99], v[184:187], v[214:217], v[96:99]
	v_mfma_f32_16x16x32_bf16 v[84:87], v[166:169], v[222:225], v[84:87]
	v_mfma_f32_16x16x32_bf16 v[80:83], v[184:187], v[222:225], v[80:83]
	v_mfma_f32_16x16x32_bf16 v[68:71], v[166:169], v[230:233], v[68:71]
	v_mfma_f32_16x16x32_bf16 v[64:67], v[184:187], v[230:233], v[64:67]
	s_setprio 0
	s_barrier
; #define PG8_STAGE(bufoff, gbase, voff) do { _Pragma("unroll") for (int _i = 0; _i < 2; ++_i) \
;         __builtin_amdgcn_global_load_lds((const unsigned*)((const char*)(gbase) + (voff)[_i]), (PG8_LAS unsigned*)(lds + (bufoff) + ldsw + _i * 8192), 16, 0, 0); } while (0)
; #define PG8_LDA(dst, b, h) do { _Pragma("unroll") for (int m = 0; m < 4; ++m) _Pragma("unroll") for (int k = 0; k < 2; ++k) dst[m][k] = *(const PG8_LAS bf16x8*)(lds + PG8_SA(b, h) + aoff + m * 2048 + k * 1024); } while (0)
; #define PG8_MMA(ai, bj, At, Bt) do { __builtin_amdgcn_s_setprio(1); _Pragma("unroll") for (int m = 0; m < 4; ++m) _Pragma("unroll") for (int n = 0; n < 2; ++n) _Pragma("unroll") for (int k = 0; k < 2; ++k) \
;         acc[ai][bj][m][n] = __builtin_amdgcn_mfma_f32_16x16x32_bf16(Bt[n][k], At[m][k], acc[ai][bj][m][n], 0, 0, 0); __builtin_amdgcn_s_setprio(0); } while (0)
; #define PG8_WAIT_V(n) asm volatile("s_waitcnt vmcnt(" #n ")" ::: "memory")
; #define PG8_WAIT_L(n) asm volatile("s_waitcnt lgkmcnt(" #n ")" ::: "memory")
; #define PG8_BAR __builtin_amdgcn_s_barrier()
; #define PG8_SCHED __builtin_amdgcn_sched_barrier(0)
; template <class Epi, class Sched, bool ALIGN_EPI = false, bool SP2 = false>
; __device__ __forceinline__ void gemm_phase(PG8_LAS unsigned char* lds, const Gemm g, const Sched& S, const Epi& E, const int tid) {
;     ...
;         for (int t = 0; t < nt; t += 2) {
;     ...
;             PG8_LDA(At, 1, 1); PG8_STAGE(PG8_SB(1, 0), b3, voffB); PG8_STAGE(PG8_SB(1, 1), b3 + hstep, voffB); PG8_STAGE(PG8_SA(1, 0), a3, voffA);
;             PG8_WAIT_V(8); PG8_WAIT_L(0); PG8_BAR; PG8_MMA(1, 0, At, B0); PG8_MMA(1, 1, At, B1); PG8_BAR; PG8_SCHED;
	s_add_i32 s30, s45, s46
	v_lshl_add_u64 v[158:159], v[158:159], 0, s[28:29]
	s_mov_b32 m0, s30
	ds_read_b128 v[188:191], v145 offset:49152
	ds_read_b128 v[192:195], v145 offset:50176
	ds_read_b128 v[208:211], v145 offset:51200
	ds_read_b128 v[214:217], v145 offset:52224
	ds_read_b128 v[218:221], v145 offset:53248
	ds_read_b128 v[222:225], v145 offset:54272
	ds_read_b128 v[226:229], v145 offset:55296
	ds_read_b128 v[230:233], v145 offset:56320
	global_load_lds_dwordx4 v[158:159], off
	v_lshl_add_u64 v[158:159], v[174:175], 0, s[28:29]
	s_add_i32 m0, s30, 0x2000
	s_add_i32 s30, s63, s46
	global_load_lds_dwordx4 v[158:159], off
	v_lshl_add_u64 v[158:159], v[178:179], 0, s[28:29]
	s_mov_b32 m0, s30
	s_nop 0
	global_load_lds_dwordx4 v[158:159], off
	v_lshl_add_u64 v[158:159], v[180:181], 0, s[28:29]
	s_add_i32 m0, s30, 0x2000
	s_nop 0
	global_load_lds_dwordx4 v[158:159], off
	v_lshl_add_u64 v[158:159], v[196:197], 0, s[28:29]
	s_mov_b32 m0, s51
	s_nop 0
	global_load_lds_dwordx4 v[158:159], off
	v_lshl_add_u64 v[158:159], v[198:199], 0, s[28:29]
	s_mov_b32 m0, s52
	s_nop 0
	global_load_lds_dwordx4 v[158:159], off
	s_waitcnt vmcnt(8)
	s_waitcnt lgkmcnt(0)
	s_barrier
	s_setprio 1
	s_waitcnt lgkmcnt(0)
	v_mfma_f32_16x16x32_bf16 v[60:63], v[138:141], v[188:191], v[60:63]
	v_mfma_f32_16x16x32_bf16 v[56:59], v[150:153], v[188:191], v[56:59]
	v_mfma_f32_16x16x32_bf16 v[44:47], v[138:141], v[208:211], v[44:47]
	v_mfma_f32_16x16x32_bf16 v[40:43], v[150:153], v[208:211], v[40:43]
	v_mfma_f32_16x16x32_bf16 v[28:31], v[138:141], v[218:221], v[28:31]
	v_mfma_f32_16x16x32_bf16 v[24:27], v[150:153], v[218:221], v[24:27]
	v_mfma_f32_16x16x32_bf16 v[12:15], v[138:141], v[226:229], v[12:15]
	v_mfma_f32_16x16x32_bf16 v[8:11], v[150:153], v[226:229], v[8:11]
	v_mfma_f32_16x16x32_bf16 v[60:63], v[146:149], v[192:195], v[60:63]
	v_mfma_f32_16x16x32_bf16 v[56:59], v[154:157], v[192:195], v[56:59]
	v_mfma_f32_16x16x32_bf16 v[44:47], v[146:149], v[214:217], v[44:47]
	v_mfma_f32_16x16x32_bf16 v[40:43], v[154:157], v[214:217], v[40:43]
	v_mfma_f32_16x16x32_bf16 v[28:31], v[146:149], v[222:225], v[28:31]
	v_mfma_f32_16x16x32_bf16 v[24:27], v[154:157], v[222:225], v[24:27]
	v_mfma_f32_16x16x32_bf16 v[12:15], v[146:149], v[230:233], v[12:15]
	v_mfma_f32_16x16x32_bf16 v[8:11], v[154:157], v[230:233], v[8:11]
	s_setprio 0
	s_setprio 1
	v_mfma_f32_16x16x32_bf16 v[52:55], v[162:165], v[188:191], v[52:55]
	v_mfma_f32_16x16x32_bf16 v[48:51], v[170:173], v[188:191], v[48:51]
	v_mfma_f32_16x16x32_bf16 v[36:39], v[162:165], v[208:211], v[36:39]
	v_mfma_f32_16x16x32_bf16 v[32:35], v[170:173], v[208:211], v[32:35]
	v_mfma_f32_16x16x32_bf16 v[20:23], v[162:165], v[218:221], v[20:23]
	v_mfma_f32_16x16x32_bf16 v[16:19], v[170:173], v[218:221], v[16:19]
	v_mfma_f32_16x16x32_bf16 v[4:7], v[162:165], v[226:229], v[4:7]
	v_mfma_f32_16x16x32_bf16 v[0:3], v[170:173], v[226:229], v[0:3]
	v_mfma_f32_16x16x32_bf16 v[52:55], v[166:169], v[192:195], v[52:55]
	v_mfma_f32_16x16x32_bf16 v[48:51], v[184:187], v[192:195], v[48:51]
	v_mfma_f32_16x16x32_bf16 v[36:39], v[166:169], v[214:217], v[36:39]
	v_mfma_f32_16x16x32_bf16 v[32:35], v[184:187], v[214:217], v[32:35]
	v_mfma_f32_16x16x32_bf16 v[20:23], v[166:169], v[222:225], v[20:23]
	v_mfma_f32_16x16x32_bf16 v[16:19], v[184:187], v[222:225], v[16:19]
	v_mfma_f32_16x16x32_bf16 v[4:7], v[166:169], v[230:233], v[4:7]
	v_mfma_f32_16x16x32_bf16 v[0:3], v[184:187], v[230:233], v[0:3]
	s_setprio 0
	s_barrier
	s_add_u32 s26, s26, 0x100
	s_addc_u32 s27, s27, 0
	s_add_u32 s36, s36, 0x100
	s_addc_u32 s37, s37, 0
	s_cmp_ge_u32 s44, s57
	s_mov_b32 s30, s44
	s_cbranch_scc1 .Lmy_kdone_0

; #define PG8_BAR __builtin_amdgcn_s_barrier()
; template <class Epi, class Sched, bool ALIGN_EPI = false, bool SP2 = false>
; __device__ __forceinline__ void gemm_phase(PG8_LAS unsigned char* lds, const Gemm g, const Sched& S, const Epi& E, const int tid) {
;     ...
;         if constexpr (ALIGN_EPI) { if (wr == 0) PG8_BAR; }
.Lmy_kdone_0:
	s_and_b64 vcc, exec, s[18:19]
	s_cbranch_vccz .LBB0_63
	s_barrier

; #define PG8_STAGE(bufoff, gbase, voff) do { _Pragma("unroll") for (int _i = 0; _i < 2; ++_i) \
;         __builtin_amdgcn_global_load_lds((const unsigned*)((const char*)(gbase) + (voff)[_i]), (PG8_LAS unsigned*)(lds + (bufoff) + ldsw + _i * 8192), 16, 0, 0); } while (0)
; #define PG8_LDA(dst, b, h) do { _Pragma("unroll") for (int m = 0; m < 4; ++m) _Pragma("unroll") for (int k = 0; k < 2; ++k) dst[m][k] = *(const PG8_LAS bf16x8*)(lds + PG8_SA(b, h) + aoff + m * 2048 + k * 1024); } while (0)
; #define PG8_LDB(dst, b, h) do { _Pragma("unroll") for (int n = 0; n < 2; ++n) _Pragma("unroll") for (int k = 0; k < 2; ++k) dst[n][k] = *(const PG8_LAS bf16x8*)(lds + PG8_SB(b, h) + boff + n * 2048 + k * 1024); } while (0)
; #define PG8_WAIT_V(n) asm volatile("s_waitcnt vmcnt(" #n ")" ::: "memory")
; #define PG8_WAIT_L(n) asm volatile("s_waitcnt lgkmcnt(" #n ")" ::: "memory")
; #define PG8_BAR __builtin_amdgcn_s_barrier()
; #define PG8_SCHED __builtin_amdgcn_sched_barrier(0)
; template <class Epi, class Sched, bool ALIGN_EPI = false, bool SP2 = false>
; __device__ __forceinline__ void gemm_phase(PG8_LAS unsigned char* lds, const Gemm g, const Sched& S, const Epi& E, const int tid) {
;     ...
;         const bool has_next = S.next(ui + 1, nxt);
;         const char* nA = has_next ? (const char*)g.A + (size_t)nxt.pm * tstep : cA; const char* nB = has_next ? (const char*)g.Bt + (size_t)nxt.pn * tstep : cB;
;         for (int t = 0; t < nt; t += 2) {
;             const bool last = (t == nt - 2);
;             const char* a1 = cA + (size_t)(t + 1) * kstep;
;             const char* a2 = last ? nA : cA + (size_t)(t + 2) * kstep; const char* b2 = last ? nB : cB + (size_t)(t + 2) * kstep;
;             const char* a3 = a2 + kstep; const char* b3 = b2 + kstep;
;             if (last && has_next) S.a_ready(nxt);
;             if constexpr (SP2) {
;             PG8_LDB(B0, 0, 0); PG8_LDB(B1, 0, 1); PG8_SCHED; PG8_LDA(At, 0, 0); PG8_STAGE(PG8_SA(1, 1), a1 + hstep, voffA);
;             PG8_WAIT_V(8); PG8_WAIT_L(0); PG8_BAR; PG8_MMA(0, 0, At, B0); PG8_MMA(0, 1, At, B1); PG8_BAR; PG8_SCHED;
;             PG8_LDA(At, 0, 1); PG8_STAGE(PG8_SB(0, 0), b2, voffB); PG8_STAGE(PG8_SB(0, 1), b2 + hstep, voffB); PG8_STAGE(PG8_SA(0, 0), a2, voffA);
;             PG8_WAIT_V(8); PG8_WAIT_L(0); PG8_BAR; PG8_MMA(1, 0, At, B0); PG8_MMA(1, 1, At, B1); PG8_BAR; PG8_SCHED;
.LBB0_466:
	s_ashr_i32 s51, s50, 31
	s_lshl_b64 s[20:21], s[50:51], 19
	s_add_u32 s52, s12, s20
	s_addc_u32 s53, s13, s21
	s_and_b64 s[20:21], s[40:41], exec
	s_cselect_b32 s1, s53, s15
	s_cselect_b32 s36, s52, s14
	s_ashr_i32 s49, s48, 31
	s_lshl_b64 s[20:21], s[48:49], 19
	s_add_u32 s68, s22, s20
	s_addc_u32 s69, s23, s21
	s_and_b64 s[20:21], s[40:41], exec
	s_cselect_b32 s37, s69, s17
	s_cselect_b32 s42, s68, s16
	s_add_u32 s14, s14, 0x40080
	s_addc_u32 s15, s15, 0
	s_add_u32 s43, s16, 0x100
	s_addc_u32 s49, s17, 0
	s_mov_b32 s51, -2
	s_add_u32 s16, s14, 0xfffc0080
	s_addc_u32 s17, s15, -1
	s_add_i32 s56, 0, 0x10000
	s_cmp_eq_u32 s51, 12
	s_cselect_b32 s21, s1, s17
	s_cselect_b32 s20, s36, s16
	v_add_u32_e32 v138, s56, v147
	s_cselect_b32 s17, s37, s49
	s_cselect_b32 s16, s42, s43
	s_add_i32 s58, 0, 0x14000
	ds_read_b128 v[140:143], v138
	ds_read_b128 v[154:157], v138 offset:1024
	ds_read_b128 v[162:165], v138 offset:2048
	ds_read_b128 v[166:169], v138 offset:3072
	v_add_u32_e32 v138, s58, v147
	ds_read_b128 v[170:173], v138
	ds_read_b128 v[184:187], v138 offset:1024
	ds_read_b128 v[188:191], v138 offset:2048
	ds_read_b128 v[192:195], v138 offset:3072
	v_lshl_add_u64 v[158:159], s[14:15], 0, v[134:135]
	s_add_i32 m0, s3, 0xc000
	ds_read_b128 v[208:211], v153
	ds_read_b128 v[214:217], v153 offset:1024
	ds_read_b128 v[218:221], v153 offset:2048
	ds_read_b128 v[222:225], v153 offset:3072
	ds_read_b128 v[226:229], v153 offset:4096
	ds_read_b128 v[230:233], v153 offset:5120
	ds_read_b128 v[234:237], v153 offset:6144
	ds_read_b128 v[238:241], v153 offset:7168
	global_load_lds_dwordx4 v[158:159], off
	v_lshl_add_u64 v[158:159], s[14:15], 0, v[136:137]
	s_add_i32 m0, s3, 0xe000
	s_nop 0
	global_load_lds_dwordx4 v[158:159], off
	s_waitcnt vmcnt(24)
	s_waitcnt lgkmcnt(0)
	s_barrier
	s_setprio 1
	s_waitcnt lgkmcnt(0)
	v_mfma_f32_16x16x32_bf16 v[124:127], v[140:143], v[208:211], 0
	v_mfma_f32_16x16x32_bf16 v[120:123], v[162:165], v[208:211], 0
	v_mfma_f32_16x16x32_bf16 v[108:111], v[140:143], v[218:221], 0
	v_mfma_f32_16x16x32_bf16 v[104:107], v[162:165], v[218:221], 0
	v_mfma_f32_16x16x32_bf16 v[92:95], v[140:143], v[226:229], 0
	v_mfma_f32_16x16x32_bf16 v[88:91], v[162:165], v[226:229], 0
	v_mfma_f32_16x16x32_bf16 v[76:79], v[140:143], v[234:237], 0
	v_mfma_f32_16x16x32_bf16 v[72:75], v[162:165], v[234:237], 0
	v_mfma_f32_16x16x32_bf16 v[124:127], v[154:157], v[214:217], v[124:127]
	v_mfma_f32_16x16x32_bf16 v[120:123], v[166:169], v[214:217], v[120:123]
	v_mfma_f32_16x16x32_bf16 v[108:111], v[154:157], v[222:225], v[108:111]
	v_mfma_f32_16x16x32_bf16 v[104:107], v[166:169], v[222:225], v[104:107]
	v_mfma_f32_16x16x32_bf16 v[92:95], v[154:157], v[230:233], v[92:95]
	v_mfma_f32_16x16x32_bf16 v[88:91], v[166:169], v[230:233], v[88:91]
	v_mfma_f32_16x16x32_bf16 v[76:79], v[154:157], v[238:241], v[76:79]
	v_mfma_f32_16x16x32_bf16 v[72:75], v[166:169], v[238:241], v[72:75]
	s_setprio 0
	s_setprio 1
	v_mfma_f32_16x16x32_bf16 v[116:119], v[170:173], v[208:211], 0
	v_mfma_f32_16x16x32_bf16 v[112:115], v[188:191], v[208:211], 0
	v_mfma_f32_16x16x32_bf16 v[100:103], v[170:173], v[218:221], 0
	v_mfma_f32_16x16x32_bf16 v[96:99], v[188:191], v[218:221], 0
	v_mfma_f32_16x16x32_bf16 v[84:87], v[170:173], v[226:229], 0
	v_mfma_f32_16x16x32_bf16 v[80:83], v[188:191], v[226:229], 0
	v_mfma_f32_16x16x32_bf16 v[68:71], v[170:173], v[234:237], 0
	v_mfma_f32_16x16x32_bf16 v[64:67], v[188:191], v[234:237], 0
	v_mfma_f32_16x16x32_bf16 v[116:119], v[184:187], v[214:217], v[116:119]
	v_mfma_f32_16x16x32_bf16 v[112:115], v[192:195], v[214:217], v[112:115]
	v_mfma_f32_16x16x32_bf16 v[100:103], v[184:187], v[222:225], v[100:103]
	v_mfma_f32_16x16x32_bf16 v[96:99], v[192:195], v[222:225], v[96:99]
	v_mfma_f32_16x16x32_bf16 v[84:87], v[184:187], v[230:233], v[84:87]
	v_mfma_f32_16x16x32_bf16 v[80:83], v[192:195], v[230:233], v[80:83]
	v_mfma_f32_16x16x32_bf16 v[68:71], v[184:187], v[238:241], v[68:71]
	v_mfma_f32_16x16x32_bf16 v[64:67], v[192:195], v[238:241], v[64:67]
	s_setprio 0
	s_barrier
	s_add_i32 s56, s56, s27
	v_lshl_add_u64 v[158:159], s[16:17], 0, v[160:161]
	s_mov_b32 m0, s56
	ds_read_b128 v[208:211], v153 offset:16384
	ds_read_b128 v[214:217], v153 offset:17408
	ds_read_b128 v[218:221], v153 offset:18432
	ds_read_b128 v[222:225], v153 offset:19456
	ds_read_b128 v[226:229], v153 offset:20480
	ds_read_b128 v[230:233], v153 offset:21504
	ds_read_b128 v[234:237], v153 offset:22528
	ds_read_b128 v[238:241], v153 offset:23552
	global_load_lds_dwordx4 v[158:159], off
	s_add_i32 m0, s56, 0x2000
	s_add_u32 s56, s16, 0x40000
	v_lshl_add_u64 v[174:175], s[16:17], 0, v[132:133]
	s_addc_u32 s57, s17, 0
	s_add_i32 s58, s58, s27
	global_load_lds_dwordx4 v[174:175], off
	v_lshl_add_u64 v[178:179], s[56:57], 0, v[160:161]
	s_mov_b32 m0, s58
	v_lshl_add_u64 v[180:181], s[20:21], 0, v[130:131]
	global_load_lds_dwordx4 v[178:179], off
	v_lshl_add_u64 v[178:179], s[56:57], 0, v[132:133]
	s_add_i32 m0, s58, 0x2000
	s_nop 0
	global_load_lds_dwordx4 v[178:179], off
	v_lshl_add_u64 v[178:179], s[20:21], 0, v[128:129]
	s_mov_b32 m0, s3
	s_nop 0
	global_load_lds_dwordx4 v[178:179], off
	s_mov_b32 m0, s30
	s_nop 0
	global_load_lds_dwordx4 v[180:181], off
	s_cmp_lt_u32 s83, 2
	s_cbranch_scc1 .Lmy_w8_1
	s_waitcnt vmcnt(24)
	s_branch .Lmy_wj_1

; #define PG8_STAGE(bufoff, gbase, voff) do { _Pragma("unroll") for (int _i = 0; _i < 2; ++_i) \
;         __builtin_amdgcn_global_load_lds((const unsigned*)((const char*)(gbase) + (voff)[_i]), (PG8_LAS unsigned*)(lds + (bufoff) + ldsw + _i * 8192), 16, 0, 0); } while (0)
; #define PG8_LDA(dst, b, h) do { _Pragma("unroll") for (int m = 0; m < 4; ++m) _Pragma("unroll") for (int k = 0; k < 2; ++k) dst[m][k] = *(const PG8_LAS bf16x8*)(lds + PG8_SA(b, h) + aoff + m * 2048 + k * 1024); } while (0)
; #define PG8_LDB(dst, b, h) do { _Pragma("unroll") for (int n = 0; n < 2; ++n) _Pragma("unroll") for (int k = 0; k < 2; ++k) dst[n][k] = *(const PG8_LAS bf16x8*)(lds + PG8_SB(b, h) + boff + n * 2048 + k * 1024); } while (0)
; #define PG8_MMA(ai, bj, At, Bt) do { __builtin_amdgcn_s_setprio(1); _Pragma("unroll") for (int m = 0; m < 4; ++m) _Pragma("unroll") for (int n = 0; n < 2; ++n) _Pragma("unroll") for (int k = 0; k < 2; ++k) \
;         acc[ai][bj][m][n] = __builtin_amdgcn_mfma_f32_16x16x32_bf16(Bt[n][k], At[m][k], acc[ai][bj][m][n], 0, 0, 0); __builtin_amdgcn_s_setprio(0); } while (0)
; #define PG8_WAIT_V(n) asm volatile("s_waitcnt vmcnt(" #n ")" ::: "memory")
; #define PG8_WAIT_L(n) asm volatile("s_waitcnt lgkmcnt(" #n ")" ::: "memory")
; #define PG8_BAR __builtin_amdgcn_s_barrier()
; #define PG8_SCHED __builtin_amdgcn_sched_barrier(0)
; template <class Epi, class Sched, bool ALIGN_EPI = false, bool SP2 = false>
; __device__ __forceinline__ void gemm_phase(PG8_LAS unsigned char* lds, const Gemm g, const Sched& S, const Epi& E, const int tid) {
;     ...
;             PG8_WAIT_V(8); PG8_WAIT_L(0); PG8_BAR; PG8_MMA(1, 0, At, B0); PG8_MMA(1, 1, At, B1); PG8_BAR; PG8_SCHED;
;             PG8_LDB(B0, 1, 0); PG8_LDB(B1, 1, 1); PG8_SCHED; PG8_LDA(At, 1, 0); PG8_STAGE(PG8_SA(0, 1), a2 + hstep, voffA);
;             PG8_WAIT_V(8); PG8_WAIT_L(0); PG8_BAR; PG8_MMA(0, 0, At, B0); PG8_MMA(0, 1, At, B1); PG8_BAR; PG8_SCHED;
.Lmy_wj_1:
	s_waitcnt lgkmcnt(0)
	s_barrier
	s_setprio 1
	s_waitcnt lgkmcnt(0)
	v_mfma_f32_16x16x32_bf16 v[60:63], v[140:143], v[208:211], 0
	v_mfma_f32_16x16x32_bf16 v[56:59], v[162:165], v[208:211], 0
	v_mfma_f32_16x16x32_bf16 v[44:47], v[140:143], v[218:221], 0
	v_mfma_f32_16x16x32_bf16 v[40:43], v[162:165], v[218:221], 0
	v_mfma_f32_16x16x32_bf16 v[28:31], v[140:143], v[226:229], 0
	v_mfma_f32_16x16x32_bf16 v[24:27], v[162:165], v[226:229], 0
	v_mfma_f32_16x16x32_bf16 v[12:15], v[140:143], v[234:237], 0
	v_mfma_f32_16x16x32_bf16 v[8:11], v[162:165], v[234:237], 0
	v_mfma_f32_16x16x32_bf16 v[60:63], v[154:157], v[214:217], v[60:63]
	v_mfma_f32_16x16x32_bf16 v[56:59], v[166:169], v[214:217], v[56:59]
	v_mfma_f32_16x16x32_bf16 v[44:47], v[154:157], v[222:225], v[44:47]
	v_mfma_f32_16x16x32_bf16 v[40:43], v[166:169], v[222:225], v[40:43]
	v_mfma_f32_16x16x32_bf16 v[28:31], v[154:157], v[230:233], v[28:31]
	v_mfma_f32_16x16x32_bf16 v[24:27], v[166:169], v[230:233], v[24:27]
	v_mfma_f32_16x16x32_bf16 v[12:15], v[154:157], v[238:241], v[12:15]
	v_mfma_f32_16x16x32_bf16 v[8:11], v[166:169], v[238:241], v[8:11]
	s_setprio 0
	s_setprio 1
	v_mfma_f32_16x16x32_bf16 v[52:55], v[170:173], v[208:211], 0
	v_mfma_f32_16x16x32_bf16 v[48:51], v[188:191], v[208:211], 0
	v_mfma_f32_16x16x32_bf16 v[36:39], v[170:173], v[218:221], 0
	v_mfma_f32_16x16x32_bf16 v[32:35], v[188:191], v[218:221], 0
	v_mfma_f32_16x16x32_bf16 v[20:23], v[170:173], v[226:229], 0
	v_mfma_f32_16x16x32_bf16 v[16:19], v[188:191], v[226:229], 0
	v_mfma_f32_16x16x32_bf16 v[4:7], v[170:173], v[234:237], 0
	v_mfma_f32_16x16x32_bf16 v[0:3], v[188:191], v[234:237], 0
	v_mfma_f32_16x16x32_bf16 v[52:55], v[184:187], v[214:217], v[52:55]
	v_mfma_f32_16x16x32_bf16 v[48:51], v[192:195], v[214:217], v[48:51]
	v_mfma_f32_16x16x32_bf16 v[36:39], v[184:187], v[222:225], v[36:39]
	v_mfma_f32_16x16x32_bf16 v[32:35], v[192:195], v[222:225], v[32:35]
	v_mfma_f32_16x16x32_bf16 v[20:23], v[184:187], v[230:233], v[20:23]
	v_mfma_f32_16x16x32_bf16 v[16:19], v[192:195], v[230:233], v[16:19]
	v_mfma_f32_16x16x32_bf16 v[4:7], v[184:187], v[238:241], v[4:7]
	v_mfma_f32_16x16x32_bf16 v[0:3], v[192:195], v[238:241], v[0:3]
	s_setprio 0
	s_barrier
	s_add_i32 s56, 0, 0x18000
	v_add_u32_e32 v138, s56, v147
	s_add_i32 s57, 0, 0x1c000
	ds_read_b128 v[140:143], v138
	ds_read_b128 v[154:157], v138 offset:1024
	ds_read_b128 v[162:165], v138 offset:2048
	ds_read_b128 v[166:169], v138 offset:3072
	v_add_u32_e32 v138, s57, v147
	ds_read_b128 v[170:173], v138
	ds_read_b128 v[184:187], v138 offset:1024
	ds_read_b128 v[188:191], v138 offset:2048
	ds_read_b128 v[192:195], v138 offset:3072
	s_add_u32 s20, s20, 0x40000
	s_addc_u32 s21, s21, 0
	s_mov_b32 m0, s31
	v_lshl_add_u64 v[196:197], s[20:21], 0, v[128:129]
	ds_read_b128 v[208:211], v153 offset:32768
	ds_read_b128 v[214:217], v153 offset:33792
	ds_read_b128 v[218:221], v153 offset:34816
	ds_read_b128 v[222:225], v153 offset:35840
	ds_read_b128 v[226:229], v153 offset:36864
	ds_read_b128 v[230:233], v153 offset:37888
	ds_read_b128 v[234:237], v153 offset:38912
	ds_read_b128 v[238:241], v153 offset:39936
	global_load_lds_dwordx4 v[196:197], off
	v_lshl_add_u64 v[196:197], s[20:21], 0, v[130:131]
	s_mov_b32 m0, s34
	s_nop 0
	global_load_lds_dwordx4 v[196:197], off
	s_waitcnt vmcnt(8)
	s_waitcnt lgkmcnt(0)
	s_barrier
	s_setprio 1
	s_waitcnt lgkmcnt(0)
	v_mfma_f32_16x16x32_bf16 v[124:127], v[140:143], v[208:211], v[124:127]
	v_mfma_f32_16x16x32_bf16 v[120:123], v[162:165], v[208:211], v[120:123]
	v_mfma_f32_16x16x32_bf16 v[108:111], v[140:143], v[218:221], v[108:111]
	v_mfma_f32_16x16x32_bf16 v[104:107], v[162:165], v[218:221], v[104:107]
	v_mfma_f32_16x16x32_bf16 v[92:95], v[140:143], v[226:229], v[92:95]
	v_mfma_f32_16x16x32_bf16 v[88:91], v[162:165], v[226:229], v[88:91]
	v_mfma_f32_16x16x32_bf16 v[76:79], v[140:143], v[234:237], v[76:79]
	v_mfma_f32_16x16x32_bf16 v[72:75], v[162:165], v[234:237], v[72:75]
	v_mfma_f32_16x16x32_bf16 v[124:127], v[154:157], v[214:217], v[124:127]
	v_mfma_f32_16x16x32_bf16 v[120:123], v[166:169], v[214:217], v[120:123]
	v_mfma_f32_16x16x32_bf16 v[108:111], v[154:157], v[222:225], v[108:111]
	v_mfma_f32_16x16x32_bf16 v[104:107], v[166:169], v[222:225], v[104:107]
	v_mfma_f32_16x16x32_bf16 v[92:95], v[154:157], v[230:233], v[92:95]
	v_mfma_f32_16x16x32_bf16 v[88:91], v[166:169], v[230:233], v[88:91]
	v_mfma_f32_16x16x32_bf16 v[76:79], v[154:157], v[238:241], v[76:79]
	v_mfma_f32_16x16x32_bf16 v[72:75], v[166:169], v[238:241], v[72:75]
	s_setprio 0
	s_setprio 1
	v_mfma_f32_16x16x32_bf16 v[116:119], v[170:173], v[208:211], v[116:119]
	v_mfma_f32_16x16x32_bf16 v[112:115], v[188:191], v[208:211], v[112:115]
	v_mfma_f32_16x16x32_bf16 v[100:103], v[170:173], v[218:221], v[100:103]
	v_mfma_f32_16x16x32_bf16 v[96:99], v[188:191], v[218:221], v[96:99]
	v_mfma_f32_16x16x32_bf16 v[84:87], v[170:173], v[226:229], v[84:87]
	v_mfma_f32_16x16x32_bf16 v[80:83], v[188:191], v[226:229], v[80:83]
	v_mfma_f32_16x16x32_bf16 v[68:71], v[170:173], v[234:237], v[68:71]
	v_mfma_f32_16x16x32_bf16 v[64:67], v[188:191], v[234:237], v[64:67]
	v_mfma_f32_16x16x32_bf16 v[116:119], v[184:187], v[214:217], v[116:119]
	v_mfma_f32_16x16x32_bf16 v[112:115], v[192:195], v[214:217], v[112:115]
	v_mfma_f32_16x16x32_bf16 v[100:103], v[184:187], v[222:225], v[100:103]
	v_mfma_f32_16x16x32_bf16 v[96:99], v[192:195], v[222:225], v[96:99]
	v_mfma_f32_16x16x32_bf16 v[84:87], v[184:187], v[230:233], v[84:87]
	v_mfma_f32_16x16x32_bf16 v[80:83], v[192:195], v[230:233], v[80:83]
	v_mfma_f32_16x16x32_bf16 v[68:71], v[184:187], v[238:241], v[68:71]
	v_mfma_f32_16x16x32_bf16 v[64:67], v[192:195], v[238:241], v[64:67]
	s_setprio 0
	s_barrier
; #define PG8_STAGE(bufoff, gbase, voff) do { _Pragma("unroll") for (int _i = 0; _i < 2; ++_i) \
;         __builtin_amdgcn_global_load_lds((const unsigned*)((const char*)(gbase) + (voff)[_i]), (PG8_LAS unsigned*)(lds + (bufoff) + ldsw + _i * 8192), 16, 0, 0); } while (0)
; #define PG8_LDA(dst, b, h) do { _Pragma("unroll") for (int m = 0; m < 4; ++m) _Pragma("unroll") for (int k = 0; k < 2; ++k) dst[m][k] = *(const PG8_LAS bf16x8*)(lds + PG8_SA(b, h) + aoff + m * 2048 + k * 1024); } while (0)
; #define PG8_MMA(ai, bj, At, Bt) do { __builtin_amdgcn_s_setprio(1); _Pragma("unroll") for (int m = 0; m < 4; ++m) _Pragma("unroll") for (int n = 0; n < 2; ++n) _Pragma("unroll") for (int k = 0; k < 2; ++k) \
;         acc[ai][bj][m][n] = __builtin_amdgcn_mfma_f32_16x16x32_bf16(Bt[n][k], At[m][k], acc[ai][bj][m][n], 0, 0, 0); __builtin_amdgcn_s_setprio(0); } while (0)
; #define PG8_WAIT_V(n) asm volatile("s_waitcnt vmcnt(" #n ")" ::: "memory")
; #define PG8_WAIT_L(n) asm volatile("s_waitcnt lgkmcnt(" #n ")" ::: "memory")
; #define PG8_BAR __builtin_amdgcn_s_barrier()
; #define PG8_SCHED __builtin_amdgcn_sched_barrier(0)
; template <class Epi, class Sched, bool ALIGN_EPI = false, bool SP2 = false>
; __device__ __forceinline__ void gemm_phase(PG8_LAS unsigned char* lds, const Gemm g, const Sched& S, const Epi& E, const int tid) {
;     ...
;         for (int t = 0; t < nt; t += 2) {
;     ...
;             PG8_LDA(At, 1, 1); PG8_STAGE(PG8_SB(1, 0), b3, voffB); PG8_STAGE(PG8_SB(1, 1), b3 + hstep, voffB); PG8_STAGE(PG8_SA(1, 0), a3, voffA);
;             PG8_WAIT_V(8); PG8_WAIT_L(0); PG8_BAR; PG8_MMA(1, 0, At, B0); PG8_MMA(1, 1, At, B1); PG8_BAR; PG8_SCHED;
	s_add_i32 s20, s56, s27
	v_lshl_add_u64 v[158:159], v[158:159], 0, s[28:29]
	s_mov_b32 m0, s20
	ds_read_b128 v[208:211], v153 offset:49152
	ds_read_b128 v[214:217], v153 offset:50176
	ds_read_b128 v[218:221], v153 offset:51200
	ds_read_b128 v[222:225], v153 offset:52224
	ds_read_b128 v[226:229], v153 offset:53248
	ds_read_b128 v[230:233], v153 offset:54272
	ds_read_b128 v[234:237], v153 offset:55296
	ds_read_b128 v[238:241], v153 offset:56320
	global_load_lds_dwordx4 v[158:159], off
	s_add_i32 m0, s20, 0x2000
	s_add_u32 s16, s16, 0x40080
	v_lshl_add_u64 v[158:159], v[174:175], 0, s[28:29]
	s_addc_u32 s17, s17, 0
	s_add_i32 s20, s57, s27
	global_load_lds_dwordx4 v[158:159], off
	v_lshl_add_u64 v[158:159], s[16:17], 0, v[160:161]
	s_mov_b32 m0, s20
	s_nop 0
	global_load_lds_dwordx4 v[158:159], off
	v_lshl_add_u64 v[158:159], s[16:17], 0, v[132:133]
	s_add_i32 m0, s20, 0x2000
	s_nop 0
	global_load_lds_dwordx4 v[158:159], off
	v_lshl_add_u64 v[158:159], v[178:179], 0, s[28:29]
	s_mov_b32 m0, s81
	s_nop 0
	global_load_lds_dwordx4 v[158:159], off
	v_lshl_add_u64 v[158:159], v[180:181], 0, s[28:29]
	s_mov_b32 m0, s82
	s_nop 0
	global_load_lds_dwordx4 v[158:159], off
	s_waitcnt vmcnt(8)
	s_waitcnt lgkmcnt(0)
	s_barrier
	s_setprio 1
	s_waitcnt lgkmcnt(0)
	v_mfma_f32_16x16x32_bf16 v[60:63], v[140:143], v[208:211], v[60:63]
	v_mfma_f32_16x16x32_bf16 v[56:59], v[162:165], v[208:211], v[56:59]
	v_mfma_f32_16x16x32_bf16 v[44:47], v[140:143], v[218:221], v[44:47]
	v_mfma_f32_16x16x32_bf16 v[40:43], v[162:165], v[218:221], v[40:43]
	v_mfma_f32_16x16x32_bf16 v[28:31], v[140:143], v[226:229], v[28:31]
	v_mfma_f32_16x16x32_bf16 v[24:27], v[162:165], v[226:229], v[24:27]
	v_mfma_f32_16x16x32_bf16 v[12:15], v[140:143], v[234:237], v[12:15]
	v_mfma_f32_16x16x32_bf16 v[8:11], v[162:165], v[234:237], v[8:11]
	v_mfma_f32_16x16x32_bf16 v[60:63], v[154:157], v[214:217], v[60:63]
	v_mfma_f32_16x16x32_bf16 v[56:59], v[166:169], v[214:217], v[56:59]
	v_mfma_f32_16x16x32_bf16 v[44:47], v[154:157], v[222:225], v[44:47]
	v_mfma_f32_16x16x32_bf16 v[40:43], v[166:169], v[222:225], v[40:43]
	v_mfma_f32_16x16x32_bf16 v[28:31], v[154:157], v[230:233], v[28:31]
	v_mfma_f32_16x16x32_bf16 v[24:27], v[166:169], v[230:233], v[24:27]
	v_mfma_f32_16x16x32_bf16 v[12:15], v[154:157], v[238:241], v[12:15]
	v_mfma_f32_16x16x32_bf16 v[8:11], v[166:169], v[238:241], v[8:11]
	s_setprio 0
	s_setprio 1
	v_mfma_f32_16x16x32_bf16 v[52:55], v[170:173], v[208:211], v[52:55]
	v_mfma_f32_16x16x32_bf16 v[48:51], v[188:191], v[208:211], v[48:51]
	v_mfma_f32_16x16x32_bf16 v[36:39], v[170:173], v[218:221], v[36:39]
	v_mfma_f32_16x16x32_bf16 v[32:35], v[188:191], v[218:221], v[32:35]
	v_mfma_f32_16x16x32_bf16 v[20:23], v[170:173], v[226:229], v[20:23]
	v_mfma_f32_16x16x32_bf16 v[16:19], v[188:191], v[226:229], v[16:19]
	v_mfma_f32_16x16x32_bf16 v[4:7], v[170:173], v[234:237], v[4:7]
	v_mfma_f32_16x16x32_bf16 v[0:3], v[188:191], v[234:237], v[0:3]
	v_mfma_f32_16x16x32_bf16 v[52:55], v[184:187], v[214:217], v[52:55]
	v_mfma_f32_16x16x32_bf16 v[48:51], v[192:195], v[214:217], v[48:51]
	v_mfma_f32_16x16x32_bf16 v[36:39], v[184:187], v[222:225], v[36:39]
	v_mfma_f32_16x16x32_bf16 v[32:35], v[192:195], v[222:225], v[32:35]
	v_mfma_f32_16x16x32_bf16 v[20:23], v[184:187], v[230:233], v[20:23]
	v_mfma_f32_16x16x32_bf16 v[16:19], v[192:195], v[230:233], v[16:19]
	v_mfma_f32_16x16x32_bf16 v[4:7], v[184:187], v[238:241], v[4:7]
	v_mfma_f32_16x16x32_bf16 v[0:3], v[192:195], v[238:241], v[0:3]
	s_setprio 0
	s_barrier
	s_add_i32 s51, s51, 2
	s_add_u32 s14, s14, 0x100
	s_addc_u32 s15, s15, 0
	s_add_u32 s43, s43, 0x100
	s_addc_u32 s49, s49, 0
	s_cmp_gt_u32 s51, 13
	s_cbranch_scc1 .Lmy_kdone_1

; #define PG8_BAR __builtin_amdgcn_s_barrier()
; template <class Epi, class Sched, bool ALIGN_EPI = false, bool SP2 = false>
; __device__ __forceinline__ void gemm_phase(PG8_LAS unsigned char* lds, const Gemm g, const Sched& S, const Epi& E, const int tid) {
;     ...
;         if constexpr (ALIGN_EPI) { if (wr == 0) PG8_BAR; }
.Lmy_kdone_1:
	s_and_b64 vcc, exec, s[44:45]
	s_cbranch_vccz .LBB0_470
	s_barrier

; #define PG8_STAGE(bufoff, gbase, voff) do { _Pragma("unroll") for (int _i = 0; _i < 2; ++_i) \
;         __builtin_amdgcn_global_load_lds((const unsigned*)((const char*)(gbase) + (voff)[_i]), (PG8_LAS unsigned*)(lds + (bufoff) + ldsw + _i * 8192), 16, 0, 0); } while (0)
; #define PG8_LDA(dst, b, h) do { _Pragma("unroll") for (int m = 0; m < 4; ++m) _Pragma("unroll") for (int k = 0; k < 2; ++k) dst[m][k] = *(const PG8_LAS bf16x8*)(lds + PG8_SA(b, h) + aoff + m * 2048 + k * 1024); } while (0)
; #define PG8_LDB(dst, b, h) do { _Pragma("unroll") for (int n = 0; n < 2; ++n) _Pragma("unroll") for (int k = 0; k < 2; ++k) dst[n][k] = *(const PG8_LAS bf16x8*)(lds + PG8_SB(b, h) + boff + n * 2048 + k * 1024); } while (0)
; #define PG8_WAIT_V(n) asm volatile("s_waitcnt vmcnt(" #n ")" ::: "memory")
; #define PG8_WAIT_L(n) asm volatile("s_waitcnt lgkmcnt(" #n ")" ::: "memory")
; #define PG8_BAR __builtin_amdgcn_s_barrier()
; #define PG8_SCHED __builtin_amdgcn_sched_barrier(0)
; template <class Epi, class Sched, bool ALIGN_EPI = false, bool SP2 = false>
; __device__ __forceinline__ void gemm_phase(PG8_LAS unsigned char* lds, const Gemm g, const Sched& S, const Epi& E, const int tid) {
;     ...
;         const bool has_next = S.next(ui + 1, nxt);
;         const char* nA = has_next ? (const char*)g.A + (size_t)nxt.pm * tstep : cA; const char* nB = has_next ? (const char*)g.Bt + (size_t)nxt.pn * tstep : cB;
;         for (int t = 0; t < nt; t += 2) {
;             const bool last = (t == nt - 2);
;             const char* a1 = cA + (size_t)(t + 1) * kstep;
;             const char* a2 = last ? nA : cA + (size_t)(t + 2) * kstep; const char* b2 = last ? nB : cB + (size_t)(t + 2) * kstep;
;             const char* a3 = a2 + kstep; const char* b3 = b2 + kstep;
;             if (last && has_next) S.a_ready(nxt);
;             if constexpr (SP2) {
;             PG8_LDB(B0, 0, 0); PG8_LDB(B1, 0, 1); PG8_SCHED; PG8_LDA(At, 0, 0); PG8_STAGE(PG8_SA(1, 1), a1 + hstep, voffA);
;             PG8_WAIT_V(8); PG8_WAIT_L(0); PG8_BAR; PG8_MMA(0, 0, At, B0); PG8_MMA(0, 1, At, B1); PG8_BAR; PG8_SCHED;
;             PG8_LDA(At, 0, 1); PG8_STAGE(PG8_SB(0, 0), b2, voffB); PG8_STAGE(PG8_SB(0, 1), b2 + hstep, voffB); PG8_STAGE(PG8_SA(0, 0), a2, voffA);
;             PG8_WAIT_V(8); PG8_WAIT_L(0); PG8_BAR; PG8_MMA(1, 0, At, B0); PG8_MMA(1, 1, At, B1); PG8_BAR; PG8_SCHED;
.LBB0_516:
	s_ashr_i32 s11, s10, 31
	s_lshl_b64 s[12:13], s[10:11], 19
	s_add_u32 s12, s27, s12
	s_addc_u32 s13, s26, s13
	s_and_b64 s[14:15], s[40:41], exec
	s_cselect_b32 s11, s13, s19
	s_cselect_b32 s36, s12, s18
	s_ashr_i32 s9, s8, 31
	s_lshl_b64 s[14:15], s[8:9], 19
	s_add_u32 s14, s30, s14
	s_addc_u32 s15, s31, s15
	s_and_b64 s[22:23], s[40:41], exec
	s_cselect_b32 s9, s15, s21
	s_cselect_b32 s37, s14, s20
	s_add_u32 s18, s18, 0x40080
	s_addc_u32 s19, s19, 0
	s_add_u32 s42, s20, 0x100
	s_addc_u32 s43, s21, 0
	s_mov_b32 s51, -2
	s_add_u32 s20, s18, 0xfffc0080
	s_addc_u32 s21, s19, -1
	s_add_i32 s52, 0, 0x10000
	s_cmp_eq_u32 s51, 12
	s_cselect_b32 s23, s11, s21
	s_cselect_b32 s22, s36, s20
	v_add_u32_e32 v138, s52, v141
	s_cselect_b32 s21, s9, s43
	s_cselect_b32 s20, s37, s42
	s_add_i32 s56, 0, 0x14000
	ds_read_b128 v[150:153], v138
	ds_read_b128 v[154:157], v138 offset:1024
	ds_read_b128 v[162:165], v138 offset:2048
	ds_read_b128 v[166:169], v138 offset:3072
	v_add_u32_e32 v138, s56, v141
	ds_read_b128 v[170:173], v138
	ds_read_b128 v[184:187], v138 offset:1024
	ds_read_b128 v[188:191], v138 offset:2048
	ds_read_b128 v[192:195], v138 offset:3072
	v_lshl_add_u64 v[158:159], s[18:19], 0, v[134:135]
	s_add_i32 m0, s35, 0xc000
	ds_read_b128 v[208:211], v149
	ds_read_b128 v[214:217], v149 offset:1024
	ds_read_b128 v[218:221], v149 offset:2048
	ds_read_b128 v[222:225], v149 offset:3072
	ds_read_b128 v[226:229], v149 offset:4096
	ds_read_b128 v[230:233], v149 offset:5120
	ds_read_b128 v[234:237], v149 offset:6144
	ds_read_b128 v[238:241], v149 offset:7168
	global_load_lds_dwordx4 v[158:159], off
	v_lshl_add_u64 v[158:159], s[18:19], 0, v[136:137]
	s_add_i32 m0, s35, 0xe000
	s_nop 0
	global_load_lds_dwordx4 v[158:159], off
	s_waitcnt vmcnt(16)
	s_waitcnt lgkmcnt(0)
	s_barrier
	s_setprio 1
	s_waitcnt lgkmcnt(0)
	v_mfma_f32_16x16x32_bf16 v[124:127], v[150:153], v[208:211], 0
	v_mfma_f32_16x16x32_bf16 v[116:119], v[162:165], v[208:211], 0
	v_mfma_f32_16x16x32_bf16 v[108:111], v[150:153], v[218:221], 0
	v_mfma_f32_16x16x32_bf16 v[100:103], v[162:165], v[218:221], 0
	v_mfma_f32_16x16x32_bf16 v[92:95], v[150:153], v[226:229], 0
	v_mfma_f32_16x16x32_bf16 v[84:87], v[162:165], v[226:229], 0
	v_mfma_f32_16x16x32_bf16 v[76:79], v[150:153], v[234:237], 0
	v_mfma_f32_16x16x32_bf16 v[68:71], v[162:165], v[234:237], 0
	v_mfma_f32_16x16x32_bf16 v[124:127], v[154:157], v[214:217], v[124:127]
	v_mfma_f32_16x16x32_bf16 v[116:119], v[166:169], v[214:217], v[116:119]
	v_mfma_f32_16x16x32_bf16 v[108:111], v[154:157], v[222:225], v[108:111]
	v_mfma_f32_16x16x32_bf16 v[100:103], v[166:169], v[222:225], v[100:103]
	v_mfma_f32_16x16x32_bf16 v[92:95], v[154:157], v[230:233], v[92:95]
	v_mfma_f32_16x16x32_bf16 v[84:87], v[166:169], v[230:233], v[84:87]
	v_mfma_f32_16x16x32_bf16 v[76:79], v[154:157], v[238:241], v[76:79]
	v_mfma_f32_16x16x32_bf16 v[68:71], v[166:169], v[238:241], v[68:71]
	s_setprio 0
	s_setprio 1
	v_mfma_f32_16x16x32_bf16 v[120:123], v[170:173], v[208:211], 0
	v_mfma_f32_16x16x32_bf16 v[112:115], v[188:191], v[208:211], 0
	v_mfma_f32_16x16x32_bf16 v[104:107], v[170:173], v[218:221], 0
	v_mfma_f32_16x16x32_bf16 v[96:99], v[188:191], v[218:221], 0
	v_mfma_f32_16x16x32_bf16 v[88:91], v[170:173], v[226:229], 0
	v_mfma_f32_16x16x32_bf16 v[80:83], v[188:191], v[226:229], 0
	v_mfma_f32_16x16x32_bf16 v[72:75], v[170:173], v[234:237], 0
	v_mfma_f32_16x16x32_bf16 v[64:67], v[188:191], v[234:237], 0
	v_mfma_f32_16x16x32_bf16 v[120:123], v[184:187], v[214:217], v[120:123]
	v_mfma_f32_16x16x32_bf16 v[112:115], v[192:195], v[214:217], v[112:115]
	v_mfma_f32_16x16x32_bf16 v[104:107], v[184:187], v[222:225], v[104:107]
	v_mfma_f32_16x16x32_bf16 v[96:99], v[192:195], v[222:225], v[96:99]
	v_mfma_f32_16x16x32_bf16 v[88:91], v[184:187], v[230:233], v[88:91]
	v_mfma_f32_16x16x32_bf16 v[80:83], v[192:195], v[230:233], v[80:83]
	v_mfma_f32_16x16x32_bf16 v[72:75], v[184:187], v[238:241], v[72:75]
	v_mfma_f32_16x16x32_bf16 v[64:67], v[192:195], v[238:241], v[64:67]
	s_setprio 0
	s_barrier
	s_add_i32 s52, s52, s34
	v_lshl_add_u64 v[158:159], s[20:21], 0, v[160:161]
	s_mov_b32 m0, s52
	ds_read_b128 v[208:211], v149 offset:16384
	ds_read_b128 v[214:217], v149 offset:17408
	ds_read_b128 v[218:221], v149 offset:18432
	ds_read_b128 v[222:225], v149 offset:19456
	ds_read_b128 v[226:229], v149 offset:20480
	ds_read_b128 v[230:233], v149 offset:21504
	ds_read_b128 v[234:237], v149 offset:22528
	ds_read_b128 v[238:241], v149 offset:23552
	global_load_lds_dwordx4 v[158:159], off
	s_add_i32 m0, s52, 0x2000
	s_add_u32 s52, s20, 0x40000
	v_lshl_add_u64 v[174:175], s[20:21], 0, v[132:133]
	s_addc_u32 s53, s21, 0
	s_add_i32 s56, s56, s34
	global_load_lds_dwordx4 v[174:175], off
	v_lshl_add_u64 v[178:179], s[52:53], 0, v[160:161]
	s_mov_b32 m0, s56
	v_lshl_add_u64 v[180:181], s[22:23], 0, v[130:131]
	global_load_lds_dwordx4 v[178:179], off
	v_lshl_add_u64 v[178:179], s[52:53], 0, v[132:133]
	s_add_i32 m0, s56, 0x2000
	s_nop 0
	global_load_lds_dwordx4 v[178:179], off
	v_lshl_add_u64 v[178:179], s[22:23], 0, v[128:129]
	s_mov_b32 m0, s35
	s_nop 0
	global_load_lds_dwordx4 v[178:179], off
	s_mov_b32 m0, s44
	s_nop 0
	global_load_lds_dwordx4 v[180:181], off
	s_cmp_lt_u32 s47, 2
	s_cbranch_scc1 .Lmy_w8_2
	s_waitcnt vmcnt(16)
	s_branch .Lmy_wj_2

; #define PG8_STAGE(bufoff, gbase, voff) do { _Pragma("unroll") for (int _i = 0; _i < 2; ++_i) \
;         __builtin_amdgcn_global_load_lds((const unsigned*)((const char*)(gbase) + (voff)[_i]), (PG8_LAS unsigned*)(lds + (bufoff) + ldsw + _i * 8192), 16, 0, 0); } while (0)
; #define PG8_LDA(dst, b, h) do { _Pragma("unroll") for (int m = 0; m < 4; ++m) _Pragma("unroll") for (int k = 0; k < 2; ++k) dst[m][k] = *(const PG8_LAS bf16x8*)(lds + PG8_SA(b, h) + aoff + m * 2048 + k * 1024); } while (0)
; #define PG8_LDB(dst, b, h) do { _Pragma("unroll") for (int n = 0; n < 2; ++n) _Pragma("unroll") for (int k = 0; k < 2; ++k) dst[n][k] = *(const PG8_LAS bf16x8*)(lds + PG8_SB(b, h) + boff + n * 2048 + k * 1024); } while (0)
; #define PG8_MMA(ai, bj, At, Bt) do { __builtin_amdgcn_s_setprio(1); _Pragma("unroll") for (int m = 0; m < 4; ++m) _Pragma("unroll") for (int n = 0; n < 2; ++n) _Pragma("unroll") for (int k = 0; k < 2; ++k) \
;         acc[ai][bj][m][n] = __builtin_amdgcn_mfma_f32_16x16x32_bf16(Bt[n][k], At[m][k], acc[ai][bj][m][n], 0, 0, 0); __builtin_amdgcn_s_setprio(0); } while (0)
; #define PG8_WAIT_V(n) asm volatile("s_waitcnt vmcnt(" #n ")" ::: "memory")
; #define PG8_WAIT_L(n) asm volatile("s_waitcnt lgkmcnt(" #n ")" ::: "memory")
; #define PG8_BAR __builtin_amdgcn_s_barrier()
; #define PG8_SCHED __builtin_amdgcn_sched_barrier(0)
; template <class Epi, class Sched, bool ALIGN_EPI = false, bool SP2 = false>
; __device__ __forceinline__ void gemm_phase(PG8_LAS unsigned char* lds, const Gemm g, const Sched& S, const Epi& E, const int tid) {
;     ...
;             PG8_WAIT_V(8); PG8_WAIT_L(0); PG8_BAR; PG8_MMA(1, 0, At, B0); PG8_MMA(1, 1, At, B1); PG8_BAR; PG8_SCHED;
;             PG8_LDB(B0, 1, 0); PG8_LDB(B1, 1, 1); PG8_SCHED; PG8_LDA(At, 1, 0); PG8_STAGE(PG8_SA(0, 1), a2 + hstep, voffA);
;             PG8_WAIT_V(8); PG8_WAIT_L(0); PG8_BAR; PG8_MMA(0, 0, At, B0); PG8_MMA(0, 1, At, B1); PG8_BAR; PG8_SCHED;
.Lmy_wj_2:
	s_waitcnt lgkmcnt(0)
	s_barrier
	s_setprio 1
	s_waitcnt lgkmcnt(0)
	v_mfma_f32_16x16x32_bf16 v[60:63], v[150:153], v[208:211], 0
	v_mfma_f32_16x16x32_bf16 v[52:55], v[162:165], v[208:211], 0
	v_mfma_f32_16x16x32_bf16 v[44:47], v[150:153], v[218:221], 0
	v_mfma_f32_16x16x32_bf16 v[36:39], v[162:165], v[218:221], 0
	v_mfma_f32_16x16x32_bf16 v[28:31], v[150:153], v[226:229], 0
	v_mfma_f32_16x16x32_bf16 v[20:23], v[162:165], v[226:229], 0
	v_mfma_f32_16x16x32_bf16 v[12:15], v[150:153], v[234:237], 0
	v_mfma_f32_16x16x32_bf16 v[4:7], v[162:165], v[234:237], 0
	v_mfma_f32_16x16x32_bf16 v[60:63], v[154:157], v[214:217], v[60:63]
	v_mfma_f32_16x16x32_bf16 v[52:55], v[166:169], v[214:217], v[52:55]
	v_mfma_f32_16x16x32_bf16 v[44:47], v[154:157], v[222:225], v[44:47]
	v_mfma_f32_16x16x32_bf16 v[36:39], v[166:169], v[222:225], v[36:39]
	v_mfma_f32_16x16x32_bf16 v[28:31], v[154:157], v[230:233], v[28:31]
	v_mfma_f32_16x16x32_bf16 v[20:23], v[166:169], v[230:233], v[20:23]
	v_mfma_f32_16x16x32_bf16 v[12:15], v[154:157], v[238:241], v[12:15]
	v_mfma_f32_16x16x32_bf16 v[4:7], v[166:169], v[238:241], v[4:7]
	s_setprio 0
	s_setprio 1
	v_mfma_f32_16x16x32_bf16 v[56:59], v[170:173], v[208:211], 0
	v_mfma_f32_16x16x32_bf16 v[48:51], v[188:191], v[208:211], 0
	v_mfma_f32_16x16x32_bf16 v[40:43], v[170:173], v[218:221], 0
	v_mfma_f32_16x16x32_bf16 v[32:35], v[188:191], v[218:221], 0
	v_mfma_f32_16x16x32_bf16 v[24:27], v[170:173], v[226:229], 0
	v_mfma_f32_16x16x32_bf16 v[16:19], v[188:191], v[226:229], 0
	v_mfma_f32_16x16x32_bf16 v[8:11], v[170:173], v[234:237], 0
	v_mfma_f32_16x16x32_bf16 v[0:3], v[188:191], v[234:237], 0
	v_mfma_f32_16x16x32_bf16 v[56:59], v[184:187], v[214:217], v[56:59]
	v_mfma_f32_16x16x32_bf16 v[48:51], v[192:195], v[214:217], v[48:51]
	v_mfma_f32_16x16x32_bf16 v[40:43], v[184:187], v[222:225], v[40:43]
	v_mfma_f32_16x16x32_bf16 v[32:35], v[192:195], v[222:225], v[32:35]
	v_mfma_f32_16x16x32_bf16 v[24:27], v[184:187], v[230:233], v[24:27]
	v_mfma_f32_16x16x32_bf16 v[16:19], v[192:195], v[230:233], v[16:19]
	v_mfma_f32_16x16x32_bf16 v[8:11], v[184:187], v[238:241], v[8:11]
	v_mfma_f32_16x16x32_bf16 v[0:3], v[192:195], v[238:241], v[0:3]
	s_setprio 0
	s_barrier
	s_add_i32 s52, 0, 0x18000
	v_add_u32_e32 v138, s52, v141
	s_add_i32 s53, 0, 0x1c000
	ds_read_b128 v[150:153], v138
	ds_read_b128 v[154:157], v138 offset:1024
	ds_read_b128 v[162:165], v138 offset:2048
	ds_read_b128 v[166:169], v138 offset:3072
	v_add_u32_e32 v138, s53, v141
	ds_read_b128 v[170:173], v138
	ds_read_b128 v[184:187], v138 offset:1024
	ds_read_b128 v[188:191], v138 offset:2048
	ds_read_b128 v[192:195], v138 offset:3072
	s_add_u32 s22, s22, 0x40000
	s_addc_u32 s23, s23, 0
	s_mov_b32 m0, s45
	v_lshl_add_u64 v[196:197], s[22:23], 0, v[128:129]
	ds_read_b128 v[208:211], v149 offset:32768
	ds_read_b128 v[214:217], v149 offset:33792
	ds_read_b128 v[218:221], v149 offset:34816
	ds_read_b128 v[222:225], v149 offset:35840
	ds_read_b128 v[226:229], v149 offset:36864
	ds_read_b128 v[230:233], v149 offset:37888
	ds_read_b128 v[234:237], v149 offset:38912
	ds_read_b128 v[238:241], v149 offset:39936
	global_load_lds_dwordx4 v[196:197], off
	v_lshl_add_u64 v[196:197], s[22:23], 0, v[130:131]
	s_mov_b32 m0, s46
	s_nop 0
	global_load_lds_dwordx4 v[196:197], off
	s_waitcnt vmcnt(8)
	s_waitcnt lgkmcnt(0)
	s_barrier
	s_setprio 1
	s_waitcnt lgkmcnt(0)
	v_mfma_f32_16x16x32_bf16 v[124:127], v[150:153], v[208:211], v[124:127]
	v_mfma_f32_16x16x32_bf16 v[116:119], v[162:165], v[208:211], v[116:119]
	v_mfma_f32_16x16x32_bf16 v[108:111], v[150:153], v[218:221], v[108:111]
	v_mfma_f32_16x16x32_bf16 v[100:103], v[162:165], v[218:221], v[100:103]
	v_mfma_f32_16x16x32_bf16 v[92:95], v[150:153], v[226:229], v[92:95]
	v_mfma_f32_16x16x32_bf16 v[84:87], v[162:165], v[226:229], v[84:87]
	v_mfma_f32_16x16x32_bf16 v[76:79], v[150:153], v[234:237], v[76:79]
	v_mfma_f32_16x16x32_bf16 v[68:71], v[162:165], v[234:237], v[68:71]
	v_mfma_f32_16x16x32_bf16 v[124:127], v[154:157], v[214:217], v[124:127]
	v_mfma_f32_16x16x32_bf16 v[116:119], v[166:169], v[214:217], v[116:119]
	v_mfma_f32_16x16x32_bf16 v[108:111], v[154:157], v[222:225], v[108:111]
	v_mfma_f32_16x16x32_bf16 v[100:103], v[166:169], v[222:225], v[100:103]
	v_mfma_f32_16x16x32_bf16 v[92:95], v[154:157], v[230:233], v[92:95]
	v_mfma_f32_16x16x32_bf16 v[84:87], v[166:169], v[230:233], v[84:87]
	v_mfma_f32_16x16x32_bf16 v[76:79], v[154:157], v[238:241], v[76:79]
	v_mfma_f32_16x16x32_bf16 v[68:71], v[166:169], v[238:241], v[68:71]
	s_setprio 0
	s_setprio 1
	v_mfma_f32_16x16x32_bf16 v[120:123], v[170:173], v[208:211], v[120:123]
	v_mfma_f32_16x16x32_bf16 v[112:115], v[188:191], v[208:211], v[112:115]
	v_mfma_f32_16x16x32_bf16 v[104:107], v[170:173], v[218:221], v[104:107]
	v_mfma_f32_16x16x32_bf16 v[96:99], v[188:191], v[218:221], v[96:99]
	v_mfma_f32_16x16x32_bf16 v[88:91], v[170:173], v[226:229], v[88:91]
	v_mfma_f32_16x16x32_bf16 v[80:83], v[188:191], v[226:229], v[80:83]
	v_mfma_f32_16x16x32_bf16 v[72:75], v[170:173], v[234:237], v[72:75]
	v_mfma_f32_16x16x32_bf16 v[64:67], v[188:191], v[234:237], v[64:67]
	v_mfma_f32_16x16x32_bf16 v[120:123], v[184:187], v[214:217], v[120:123]
	v_mfma_f32_16x16x32_bf16 v[112:115], v[192:195], v[214:217], v[112:115]
	v_mfma_f32_16x16x32_bf16 v[104:107], v[184:187], v[222:225], v[104:107]
	v_mfma_f32_16x16x32_bf16 v[96:99], v[192:195], v[222:225], v[96:99]
	v_mfma_f32_16x16x32_bf16 v[88:91], v[184:187], v[230:233], v[88:91]
	v_mfma_f32_16x16x32_bf16 v[80:83], v[192:195], v[230:233], v[80:83]
	v_mfma_f32_16x16x32_bf16 v[72:75], v[184:187], v[238:241], v[72:75]
	v_mfma_f32_16x16x32_bf16 v[64:67], v[192:195], v[238:241], v[64:67]
	s_setprio 0
	s_barrier
; #define PG8_STAGE(bufoff, gbase, voff) do { _Pragma("unroll") for (int _i = 0; _i < 2; ++_i) \
;         __builtin_amdgcn_global_load_lds((const unsigned*)((const char*)(gbase) + (voff)[_i]), (PG8_LAS unsigned*)(lds + (bufoff) + ldsw + _i * 8192), 16, 0, 0); } while (0)
; #define PG8_LDA(dst, b, h) do { _Pragma("unroll") for (int m = 0; m < 4; ++m) _Pragma("unroll") for (int k = 0; k < 2; ++k) dst[m][k] = *(const PG8_LAS bf16x8*)(lds + PG8_SA(b, h) + aoff + m * 2048 + k * 1024); } while (0)
; #define PG8_MMA(ai, bj, At, Bt) do { __builtin_amdgcn_s_setprio(1); _Pragma("unroll") for (int m = 0; m < 4; ++m) _Pragma("unroll") for (int n = 0; n < 2; ++n) _Pragma("unroll") for (int k = 0; k < 2; ++k) \
;         acc[ai][bj][m][n] = __builtin_amdgcn_mfma_f32_16x16x32_bf16(Bt[n][k], At[m][k], acc[ai][bj][m][n], 0, 0, 0); __builtin_amdgcn_s_setprio(0); } while (0)
; #define PG8_WAIT_V(n) asm volatile("s_waitcnt vmcnt(" #n ")" ::: "memory")
; #define PG8_WAIT_L(n) asm volatile("s_waitcnt lgkmcnt(" #n ")" ::: "memory")
; #define PG8_BAR __builtin_amdgcn_s_barrier()
; #define PG8_SCHED __builtin_amdgcn_sched_barrier(0)
; template <class Epi, class Sched, bool ALIGN_EPI = false, bool SP2 = false>
; __device__ __forceinline__ void gemm_phase(PG8_LAS unsigned char* lds, const Gemm g, const Sched& S, const Epi& E, const int tid) {
;     ...
;         for (int t = 0; t < nt; t += 2) {
;     ...
;             PG8_LDA(At, 1, 1); PG8_STAGE(PG8_SB(1, 0), b3, voffB); PG8_STAGE(PG8_SB(1, 1), b3 + hstep, voffB); PG8_STAGE(PG8_SA(1, 0), a3, voffA);
;             PG8_WAIT_V(8); PG8_WAIT_L(0); PG8_BAR; PG8_MMA(1, 0, At, B0); PG8_MMA(1, 1, At, B1); PG8_BAR; PG8_SCHED;
	s_add_i32 s22, s52, s34
	v_lshl_add_u64 v[158:159], v[158:159], 0, s[28:29]
	s_mov_b32 m0, s22
	ds_read_b128 v[208:211], v149 offset:49152
	ds_read_b128 v[214:217], v149 offset:50176
	ds_read_b128 v[218:221], v149 offset:51200
	ds_read_b128 v[222:225], v149 offset:52224
	ds_read_b128 v[226:229], v149 offset:53248
	ds_read_b128 v[230:233], v149 offset:54272
	ds_read_b128 v[234:237], v149 offset:55296
	ds_read_b128 v[238:241], v149 offset:56320
	global_load_lds_dwordx4 v[158:159], off
	s_add_i32 m0, s22, 0x2000
	s_add_u32 s20, s20, 0x40080
	v_lshl_add_u64 v[158:159], v[174:175], 0, s[28:29]
	s_addc_u32 s21, s21, 0
	s_add_i32 s22, s53, s34
	global_load_lds_dwordx4 v[158:159], off
	v_lshl_add_u64 v[158:159], s[20:21], 0, v[160:161]
	s_mov_b32 m0, s22
	s_nop 0
	global_load_lds_dwordx4 v[158:159], off
	v_lshl_add_u64 v[158:159], s[20:21], 0, v[132:133]
	s_add_i32 m0, s22, 0x2000
	s_nop 0
	global_load_lds_dwordx4 v[158:159], off
	v_lshl_add_u64 v[158:159], v[178:179], 0, s[28:29]
	s_mov_b32 m0, s49
	s_nop 0
	global_load_lds_dwordx4 v[158:159], off
	v_lshl_add_u64 v[158:159], v[180:181], 0, s[28:29]
	s_mov_b32 m0, s50
	s_nop 0
	global_load_lds_dwordx4 v[158:159], off
	s_waitcnt vmcnt(8)
	s_waitcnt lgkmcnt(0)
	s_barrier
	s_setprio 1
	s_waitcnt lgkmcnt(0)
	v_mfma_f32_16x16x32_bf16 v[60:63], v[150:153], v[208:211], v[60:63]
	v_mfma_f32_16x16x32_bf16 v[52:55], v[162:165], v[208:211], v[52:55]
	v_mfma_f32_16x16x32_bf16 v[44:47], v[150:153], v[218:221], v[44:47]
	v_mfma_f32_16x16x32_bf16 v[36:39], v[162:165], v[218:221], v[36:39]
	v_mfma_f32_16x16x32_bf16 v[28:31], v[150:153], v[226:229], v[28:31]
	v_mfma_f32_16x16x32_bf16 v[20:23], v[162:165], v[226:229], v[20:23]
	v_mfma_f32_16x16x32_bf16 v[12:15], v[150:153], v[234:237], v[12:15]
	v_mfma_f32_16x16x32_bf16 v[4:7], v[162:165], v[234:237], v[4:7]
	v_mfma_f32_16x16x32_bf16 v[60:63], v[154:157], v[214:217], v[60:63]
	v_mfma_f32_16x16x32_bf16 v[52:55], v[166:169], v[214:217], v[52:55]
	v_mfma_f32_16x16x32_bf16 v[44:47], v[154:157], v[222:225], v[44:47]
	v_mfma_f32_16x16x32_bf16 v[36:39], v[166:169], v[222:225], v[36:39]
	v_mfma_f32_16x16x32_bf16 v[28:31], v[154:157], v[230:233], v[28:31]
	v_mfma_f32_16x16x32_bf16 v[20:23], v[166:169], v[230:233], v[20:23]
	v_mfma_f32_16x16x32_bf16 v[12:15], v[154:157], v[238:241], v[12:15]
	v_mfma_f32_16x16x32_bf16 v[4:7], v[166:169], v[238:241], v[4:7]
	s_setprio 0
	s_setprio 1
	v_mfma_f32_16x16x32_bf16 v[56:59], v[170:173], v[208:211], v[56:59]
	v_mfma_f32_16x16x32_bf16 v[48:51], v[188:191], v[208:211], v[48:51]
	v_mfma_f32_16x16x32_bf16 v[40:43], v[170:173], v[218:221], v[40:43]
	v_mfma_f32_16x16x32_bf16 v[32:35], v[188:191], v[218:221], v[32:35]
	v_mfma_f32_16x16x32_bf16 v[24:27], v[170:173], v[226:229], v[24:27]
	v_mfma_f32_16x16x32_bf16 v[16:19], v[188:191], v[226:229], v[16:19]
	v_mfma_f32_16x16x32_bf16 v[8:11], v[170:173], v[234:237], v[8:11]
	v_mfma_f32_16x16x32_bf16 v[0:3], v[188:191], v[234:237], v[0:3]
	v_mfma_f32_16x16x32_bf16 v[56:59], v[184:187], v[214:217], v[56:59]
	v_mfma_f32_16x16x32_bf16 v[48:51], v[192:195], v[214:217], v[48:51]
	v_mfma_f32_16x16x32_bf16 v[40:43], v[184:187], v[222:225], v[40:43]
	v_mfma_f32_16x16x32_bf16 v[32:35], v[192:195], v[222:225], v[32:35]
	v_mfma_f32_16x16x32_bf16 v[24:27], v[184:187], v[230:233], v[24:27]
	v_mfma_f32_16x16x32_bf16 v[16:19], v[192:195], v[230:233], v[16:19]
	v_mfma_f32_16x16x32_bf16 v[8:11], v[184:187], v[238:241], v[8:11]
	v_mfma_f32_16x16x32_bf16 v[0:3], v[192:195], v[238:241], v[0:3]
	s_setprio 0
	s_barrier
	s_add_i32 s51, s51, 2
	s_add_u32 s18, s18, 0x100
	s_addc_u32 s19, s19, 0
	s_add_u32 s42, s42, 0x100
	s_addc_u32 s43, s43, 0
	s_cmp_gt_u32 s51, 13
	s_cbranch_scc1 .Lmy_kdone_2

; #define PG8_BAR __builtin_amdgcn_s_barrier()
; template <class Epi, class Sched, bool ALIGN_EPI = false, bool SP2 = false>
; __device__ __forceinline__ void gemm_phase(PG8_LAS unsigned char* lds, const Gemm g, const Sched& S, const Epi& E, const int tid) {
;     ...
;         if constexpr (ALIGN_EPI) { if (wr == 0) PG8_BAR; }
.Lmy_kdone_2:
	s_and_b64 vcc, exec, s[6:7]
	s_cbranch_vccz .LBB0_520
	s_barrier

; #define PG8_STAGE(bufoff, gbase, voff) do { _Pragma("unroll") for (int _i = 0; _i < 2; ++_i) \
;         __builtin_amdgcn_global_load_lds((const unsigned*)((const char*)(gbase) + (voff)[_i]), (PG8_LAS unsigned*)(lds + (bufoff) + ldsw + _i * 8192), 16, 0, 0); } while (0)
; #define PG8_LDA(dst, b, h) do { _Pragma("unroll") for (int m = 0; m < 4; ++m) _Pragma("unroll") for (int k = 0; k < 2; ++k) dst[m][k] = *(const PG8_LAS bf16x8*)(lds + PG8_SA(b, h) + aoff + m * 2048 + k * 1024); } while (0)
; #define PG8_LDB(dst, b, h) do { _Pragma("unroll") for (int n = 0; n < 2; ++n) _Pragma("unroll") for (int k = 0; k < 2; ++k) dst[n][k] = *(const PG8_LAS bf16x8*)(lds + PG8_SB(b, h) + boff + n * 2048 + k * 1024); } while (0)
; #define PG8_WAIT_V(n) asm volatile("s_waitcnt vmcnt(" #n ")" ::: "memory")
; #define PG8_WAIT_L(n) asm volatile("s_waitcnt lgkmcnt(" #n ")" ::: "memory")
; #define PG8_BAR __builtin_amdgcn_s_barrier()
; #define PG8_SCHED __builtin_amdgcn_sched_barrier(0)
; template <class Epi, class Sched, bool ALIGN_EPI = false, bool SP2 = false>
; __device__ __forceinline__ void gemm_phase(PG8_LAS unsigned char* lds, const Gemm g, const Sched& S, const Epi& E, const int tid) {
;     ...
;         const bool has_next = S.next(ui + 1, nxt);
;         const char* nA = has_next ? (const char*)g.A + (size_t)nxt.pm * tstep : cA; const char* nB = has_next ? (const char*)g.Bt + (size_t)nxt.pn * tstep : cB;
;         for (int t = 0; t < nt; t += 2) {
;             const bool last = (t == nt - 2);
;             const char* a1 = cA + (size_t)(t + 1) * kstep;
;             const char* a2 = last ? nA : cA + (size_t)(t + 2) * kstep; const char* b2 = last ? nB : cB + (size_t)(t + 2) * kstep;
;             const char* a3 = a2 + kstep; const char* b3 = b2 + kstep;
;             if (last && has_next) S.a_ready(nxt);
;             if constexpr (SP2) {
;             PG8_LDB(B0, 0, 0); PG8_LDB(B1, 0, 1); PG8_SCHED; PG8_LDA(At, 0, 0); PG8_STAGE(PG8_SA(1, 1), a1 + hstep, voffA);
;             PG8_WAIT_V(8); PG8_WAIT_L(0); PG8_BAR; PG8_MMA(0, 0, At, B0); PG8_MMA(0, 1, At, B1); PG8_BAR; PG8_SCHED;
;             PG8_LDA(At, 0, 1); PG8_STAGE(PG8_SB(0, 0), b2, voffB); PG8_STAGE(PG8_SB(0, 1), b2 + hstep, voffB); PG8_STAGE(PG8_SA(0, 0), a2, voffA);
;             PG8_WAIT_V(8); PG8_WAIT_L(0); PG8_BAR; PG8_MMA(1, 0, At, B0); PG8_MMA(1, 1, At, B1); PG8_BAR; PG8_SCHED;
.LBB0_620:
	s_add_u32 s44, s50, 0x80
	s_addc_u32 s45, s51, 0
	s_add_u32 s37, s48, 0x100
	s_addc_u32 s50, s49, 0
	s_mov_b32 s48, 0
	s_add_i32 s51, s48, 2
	s_add_u32 vcc_lo, s44, 0x80
	s_addc_u32 s49, s45, 0
	s_cmp_eq_u32 s82, s48
	s_cselect_b32 s49, s35, s49
	s_cselect_b32 s48, s34, vcc_lo
	v_add_u32_e32 v156, s59, v174
	s_cselect_b32 vcc_hi, s47, s50
	s_cselect_b32 vcc_lo, s46, s37
	s_add_i32 s90, 0, 0x14000
	s_waitcnt lgkmcnt(0)
	ds_read_b128 v[144:147], v156
	ds_read_b128 v[148:151], v156 offset:1024
	ds_read_b128 v[152:155], v156 offset:2048
	ds_read_b128 v[184:187], v156 offset:3072
	v_add_u32_e32 v156, s90, v174
	ds_read_b128 v[188:191], v156
	ds_read_b128 v[192:195], v156 offset:1024
	ds_read_b128 v[214:217], v156 offset:2048
	ds_read_b128 v[218:221], v156 offset:3072
	v_lshl_add_u64 v[156:157], s[44:45], 0, v[140:141]
	s_add_i32 m0, s66, 0xc000
	ds_read_b128 v[222:225], v175
	ds_read_b128 v[226:229], v175 offset:1024
	ds_read_b128 v[230:233], v175 offset:2048
	ds_read_b128 v[234:237], v175 offset:3072
	ds_read_b128 v[238:241], v175 offset:4096
	ds_read_b128 v[242:245], v175 offset:5120
	ds_read_b128 v[246:249], v175 offset:6144
	ds_read_b128 v[208:211], v175 offset:7168
	global_load_lds_dwordx4 v[156:157], off
	v_lshl_add_u64 v[156:157], s[44:45], 0, v[142:143]
	s_add_i32 m0, s66, 0xe000
	s_nop 0
	global_load_lds_dwordx4 v[156:157], off
	s_waitcnt vmcnt(8)
	s_waitcnt lgkmcnt(0)
	s_barrier
	s_setprio 1
	s_waitcnt lgkmcnt(0)
	v_mfma_f32_16x16x32_bf16 v[124:127], v[144:147], v[222:225], 0
	v_mfma_f32_16x16x32_bf16 v[120:123], v[152:155], v[222:225], 0
	v_mfma_f32_16x16x32_bf16 v[108:111], v[144:147], v[230:233], 0
	v_mfma_f32_16x16x32_bf16 v[104:107], v[152:155], v[230:233], 0
	v_mfma_f32_16x16x32_bf16 v[92:95], v[144:147], v[238:241], 0
	v_mfma_f32_16x16x32_bf16 v[88:91], v[152:155], v[238:241], 0
	v_mfma_f32_16x16x32_bf16 v[76:79], v[144:147], v[246:249], 0
	v_mfma_f32_16x16x32_bf16 v[72:75], v[152:155], v[246:249], 0
	v_mfma_f32_16x16x32_bf16 v[124:127], v[148:151], v[226:229], v[124:127]
	v_mfma_f32_16x16x32_bf16 v[120:123], v[184:187], v[226:229], v[120:123]
	v_mfma_f32_16x16x32_bf16 v[108:111], v[148:151], v[234:237], v[108:111]
	v_mfma_f32_16x16x32_bf16 v[104:107], v[184:187], v[234:237], v[104:107]
	v_mfma_f32_16x16x32_bf16 v[92:95], v[148:151], v[242:245], v[92:95]
	v_mfma_f32_16x16x32_bf16 v[88:91], v[184:187], v[242:245], v[88:91]
	v_mfma_f32_16x16x32_bf16 v[76:79], v[148:151], v[208:211], v[76:79]
	v_mfma_f32_16x16x32_bf16 v[72:75], v[184:187], v[208:211], v[72:75]
	s_setprio 0
	s_setprio 1
	v_mfma_f32_16x16x32_bf16 v[116:119], v[188:191], v[222:225], 0
	v_mfma_f32_16x16x32_bf16 v[112:115], v[214:217], v[222:225], 0
	v_mfma_f32_16x16x32_bf16 v[100:103], v[188:191], v[230:233], 0
	v_mfma_f32_16x16x32_bf16 v[96:99], v[214:217], v[230:233], 0
	v_mfma_f32_16x16x32_bf16 v[84:87], v[188:191], v[238:241], 0
	v_mfma_f32_16x16x32_bf16 v[80:83], v[214:217], v[238:241], 0
	v_mfma_f32_16x16x32_bf16 v[68:71], v[188:191], v[246:249], 0
	v_mfma_f32_16x16x32_bf16 v[64:67], v[214:217], v[246:249], 0
	v_mfma_f32_16x16x32_bf16 v[116:119], v[192:195], v[226:229], v[116:119]
	v_mfma_f32_16x16x32_bf16 v[112:115], v[218:221], v[226:229], v[112:115]
	v_mfma_f32_16x16x32_bf16 v[100:103], v[192:195], v[234:237], v[100:103]
	v_mfma_f32_16x16x32_bf16 v[96:99], v[218:221], v[234:237], v[96:99]
	v_mfma_f32_16x16x32_bf16 v[84:87], v[192:195], v[242:245], v[84:87]
	v_mfma_f32_16x16x32_bf16 v[80:83], v[218:221], v[242:245], v[80:83]
	v_mfma_f32_16x16x32_bf16 v[68:71], v[192:195], v[208:211], v[68:71]
	v_mfma_f32_16x16x32_bf16 v[64:67], v[218:221], v[208:211], v[64:67]
	s_setprio 0
	s_barrier
	s_add_i32 s91, s59, s65
	v_lshl_add_u64 v[156:157], vcc, 0, v[160:161]
	s_mov_b32 m0, s91
	ds_read_b128 v[208:211], v175 offset:16384
	ds_read_b128 v[222:225], v175 offset:17408
	ds_read_b128 v[226:229], v175 offset:18432
	ds_read_b128 v[230:233], v175 offset:19456
	ds_read_b128 v[234:237], v175 offset:20480
	ds_read_b128 v[238:241], v175 offset:21504
	ds_read_b128 v[242:245], v175 offset:22528
	ds_read_b128 v[246:249], v175 offset:23552
	global_load_lds_dwordx4 v[156:157], off
	s_add_i32 m0, s91, 0x2000
	v_lshl_add_u64 v[250:251], vcc, 0, v[136:137]
	s_add_u32 vcc_lo, vcc_lo, s94
	s_addc_u32 vcc_hi, vcc_hi, 0
	s_add_i32 s90, s90, s65
	global_load_lds_dwordx4 v[250:251], off
	v_lshl_add_u64 v[178:179], vcc, 0, v[160:161]
	s_mov_b32 m0, s90
	v_lshl_add_u64 v[180:181], vcc, 0, v[136:137]
	global_load_lds_dwordx4 v[178:179], off
	s_add_i32 m0, s90, 0x2000
	v_lshl_add_u64 v[204:205], s[48:49], 0, v[132:133]
	global_load_lds_dwordx4 v[180:181], off
	s_mov_b32 m0, s66
	v_lshl_add_u64 v[196:197], s[48:49], 0, v[134:135]
	global_load_lds_dwordx4 v[204:205], off
	s_mov_b32 m0, s67
	s_nop 0
	global_load_lds_dwordx4 v[196:197], off
	s_waitcnt vmcnt(8)
	s_waitcnt lgkmcnt(0)
	s_barrier
; #define PG8_STAGE(bufoff, gbase, voff) do { _Pragma("unroll") for (int _i = 0; _i < 2; ++_i) \
;         __builtin_amdgcn_global_load_lds((const unsigned*)((const char*)(gbase) + (voff)[_i]), (PG8_LAS unsigned*)(lds + (bufoff) + ldsw + _i * 8192), 16, 0, 0); } while (0)
; #define PG8_LDA(dst, b, h) do { _Pragma("unroll") for (int m = 0; m < 4; ++m) _Pragma("unroll") for (int k = 0; k < 2; ++k) dst[m][k] = *(const PG8_LAS bf16x8*)(lds + PG8_SA(b, h) + aoff + m * 2048 + k * 1024); } while (0)
; #define PG8_LDB(dst, b, h) do { _Pragma("unroll") for (int n = 0; n < 2; ++n) _Pragma("unroll") for (int k = 0; k < 2; ++k) dst[n][k] = *(const PG8_LAS bf16x8*)(lds + PG8_SB(b, h) + boff + n * 2048 + k * 1024); } while (0)
; #define PG8_MMA(ai, bj, At, Bt) do { __builtin_amdgcn_s_setprio(1); _Pragma("unroll") for (int m = 0; m < 4; ++m) _Pragma("unroll") for (int n = 0; n < 2; ++n) _Pragma("unroll") for (int k = 0; k < 2; ++k) \
;         acc[ai][bj][m][n] = __builtin_amdgcn_mfma_f32_16x16x32_bf16(Bt[n][k], At[m][k], acc[ai][bj][m][n], 0, 0, 0); __builtin_amdgcn_s_setprio(0); } while (0)
; #define PG8_WAIT_V(n) asm volatile("s_waitcnt vmcnt(" #n ")" ::: "memory")
; #define PG8_WAIT_L(n) asm volatile("s_waitcnt lgkmcnt(" #n ")" ::: "memory")
; #define PG8_BAR __builtin_amdgcn_s_barrier()
; #define PG8_SCHED __builtin_amdgcn_sched_barrier(0)
; template <class Epi, class Sched, bool ALIGN_EPI = false, bool SP2 = false>
; __device__ __forceinline__ void gemm_phase(PG8_LAS unsigned char* lds, const Gemm g, const Sched& S, const Epi& E, const int tid) {
;     ...
;             PG8_WAIT_V(8); PG8_WAIT_L(0); PG8_BAR; PG8_MMA(1, 0, At, B0); PG8_MMA(1, 1, At, B1); PG8_BAR; PG8_SCHED;
;             PG8_LDB(B0, 1, 0); PG8_LDB(B1, 1, 1); PG8_SCHED; PG8_LDA(At, 1, 0); PG8_STAGE(PG8_SA(0, 1), a2 + hstep, voffA);
;             PG8_WAIT_V(8); PG8_WAIT_L(0); PG8_BAR; PG8_MMA(0, 0, At, B0); PG8_MMA(0, 1, At, B1); PG8_BAR; PG8_SCHED;
	s_setprio 1
	s_waitcnt lgkmcnt(0)
	v_mfma_f32_16x16x32_bf16 v[60:63], v[144:147], v[208:211], 0
	v_mfma_f32_16x16x32_bf16 v[56:59], v[152:155], v[208:211], 0
	v_mfma_f32_16x16x32_bf16 v[44:47], v[144:147], v[226:229], 0
	v_mfma_f32_16x16x32_bf16 v[40:43], v[152:155], v[226:229], 0
	v_mfma_f32_16x16x32_bf16 v[28:31], v[144:147], v[234:237], 0
	v_mfma_f32_16x16x32_bf16 v[24:27], v[152:155], v[234:237], 0
	v_mfma_f32_16x16x32_bf16 v[12:15], v[144:147], v[242:245], 0
	v_mfma_f32_16x16x32_bf16 v[8:11], v[152:155], v[242:245], 0
	v_mfma_f32_16x16x32_bf16 v[60:63], v[148:151], v[222:225], v[60:63]
	v_mfma_f32_16x16x32_bf16 v[56:59], v[184:187], v[222:225], v[56:59]
	v_mfma_f32_16x16x32_bf16 v[44:47], v[148:151], v[230:233], v[44:47]
	v_mfma_f32_16x16x32_bf16 v[40:43], v[184:187], v[230:233], v[40:43]
	v_mfma_f32_16x16x32_bf16 v[28:31], v[148:151], v[238:241], v[28:31]
	v_mfma_f32_16x16x32_bf16 v[24:27], v[184:187], v[238:241], v[24:27]
	v_mfma_f32_16x16x32_bf16 v[12:15], v[148:151], v[246:249], v[12:15]
	v_mfma_f32_16x16x32_bf16 v[8:11], v[184:187], v[246:249], v[8:11]
	s_setprio 0
	s_setprio 1
	v_mfma_f32_16x16x32_bf16 v[52:55], v[188:191], v[208:211], 0
	v_mfma_f32_16x16x32_bf16 v[48:51], v[214:217], v[208:211], 0
	v_mfma_f32_16x16x32_bf16 v[36:39], v[188:191], v[226:229], 0
	v_mfma_f32_16x16x32_bf16 v[32:35], v[214:217], v[226:229], 0
	v_mfma_f32_16x16x32_bf16 v[20:23], v[188:191], v[234:237], 0
	v_mfma_f32_16x16x32_bf16 v[16:19], v[214:217], v[234:237], 0
	v_mfma_f32_16x16x32_bf16 v[4:7], v[188:191], v[242:245], 0
	v_mfma_f32_16x16x32_bf16 v[0:3], v[214:217], v[242:245], 0
	v_mfma_f32_16x16x32_bf16 v[52:55], v[192:195], v[222:225], v[52:55]
	v_mfma_f32_16x16x32_bf16 v[48:51], v[218:221], v[222:225], v[48:51]
	v_mfma_f32_16x16x32_bf16 v[36:39], v[192:195], v[230:233], v[36:39]
	v_mfma_f32_16x16x32_bf16 v[32:35], v[218:221], v[230:233], v[32:35]
	v_mfma_f32_16x16x32_bf16 v[20:23], v[192:195], v[238:241], v[20:23]
	v_mfma_f32_16x16x32_bf16 v[16:19], v[218:221], v[238:241], v[16:19]
	v_mfma_f32_16x16x32_bf16 v[4:7], v[192:195], v[246:249], v[4:7]
	v_mfma_f32_16x16x32_bf16 v[0:3], v[218:221], v[246:249], v[0:3]
	s_setprio 0
	s_barrier
	s_add_i32 s90, 0, 0x18000
	v_add_u32_e32 v183, s90, v174
	s_add_i32 s91, 0, 0x1c000
	ds_read_b128 v[144:147], v183
	ds_read_b128 v[148:151], v183 offset:1024
	ds_read_b128 v[152:155], v183 offset:2048
	ds_read_b128 v[184:187], v183 offset:3072
	v_add_u32_e32 v183, s91, v174
	ds_read_b128 v[188:191], v183
	ds_read_b128 v[192:195], v183 offset:1024
	ds_read_b128 v[208:211], v183 offset:2048
	ds_read_b128 v[214:217], v183 offset:3072
	s_add_u32 s48, s48, s94
	s_addc_u32 s49, s49, 0
	s_mov_b32 m0, s68
	v_lshl_add_u64 v[198:199], s[48:49], 0, v[132:133]
	ds_read_b128 v[218:221], v175 offset:32768
	ds_read_b128 v[222:225], v175 offset:33792
	ds_read_b128 v[226:229], v175 offset:34816
	ds_read_b128 v[230:233], v175 offset:35840
	ds_read_b128 v[234:237], v175 offset:36864
	ds_read_b128 v[238:241], v175 offset:37888
	ds_read_b128 v[242:245], v175 offset:38912
	ds_read_b128 v[246:249], v175 offset:39936
	global_load_lds_dwordx4 v[198:199], off
	v_lshl_add_u64 v[198:199], s[48:49], 0, v[134:135]
	s_mov_b32 m0, s69
	s_nop 0
	global_load_lds_dwordx4 v[198:199], off
	s_waitcnt vmcnt(8)
	s_waitcnt lgkmcnt(0)
	s_barrier
	s_setprio 1
	s_waitcnt lgkmcnt(0)
	v_mfma_f32_16x16x32_bf16 v[124:127], v[144:147], v[218:221], v[124:127]
	v_mfma_f32_16x16x32_bf16 v[120:123], v[152:155], v[218:221], v[120:123]
	v_mfma_f32_16x16x32_bf16 v[108:111], v[144:147], v[226:229], v[108:111]
	v_mfma_f32_16x16x32_bf16 v[104:107], v[152:155], v[226:229], v[104:107]
	v_mfma_f32_16x16x32_bf16 v[92:95], v[144:147], v[234:237], v[92:95]
	v_mfma_f32_16x16x32_bf16 v[88:91], v[152:155], v[234:237], v[88:91]
	v_mfma_f32_16x16x32_bf16 v[76:79], v[144:147], v[242:245], v[76:79]
	v_mfma_f32_16x16x32_bf16 v[72:75], v[152:155], v[242:245], v[72:75]
	v_mfma_f32_16x16x32_bf16 v[124:127], v[148:151], v[222:225], v[124:127]
	v_mfma_f32_16x16x32_bf16 v[120:123], v[184:187], v[222:225], v[120:123]
	v_mfma_f32_16x16x32_bf16 v[108:111], v[148:151], v[230:233], v[108:111]
	v_mfma_f32_16x16x32_bf16 v[104:107], v[184:187], v[230:233], v[104:107]
	v_mfma_f32_16x16x32_bf16 v[92:95], v[148:151], v[238:241], v[92:95]
	v_mfma_f32_16x16x32_bf16 v[88:91], v[184:187], v[238:241], v[88:91]
	v_mfma_f32_16x16x32_bf16 v[76:79], v[148:151], v[246:249], v[76:79]
	v_mfma_f32_16x16x32_bf16 v[72:75], v[184:187], v[246:249], v[72:75]
	s_setprio 0
	s_setprio 1
	v_mfma_f32_16x16x32_bf16 v[116:119], v[188:191], v[218:221], v[116:119]
	v_mfma_f32_16x16x32_bf16 v[112:115], v[208:211], v[218:221], v[112:115]
	v_mfma_f32_16x16x32_bf16 v[100:103], v[188:191], v[226:229], v[100:103]
	v_mfma_f32_16x16x32_bf16 v[96:99], v[208:211], v[226:229], v[96:99]
	v_mfma_f32_16x16x32_bf16 v[84:87], v[188:191], v[234:237], v[84:87]
	v_mfma_f32_16x16x32_bf16 v[80:83], v[208:211], v[234:237], v[80:83]
	v_mfma_f32_16x16x32_bf16 v[68:71], v[188:191], v[242:245], v[68:71]
	v_mfma_f32_16x16x32_bf16 v[64:67], v[208:211], v[242:245], v[64:67]
	v_mfma_f32_16x16x32_bf16 v[116:119], v[192:195], v[222:225], v[116:119]
	v_mfma_f32_16x16x32_bf16 v[112:115], v[214:217], v[222:225], v[112:115]
	v_mfma_f32_16x16x32_bf16 v[100:103], v[192:195], v[230:233], v[100:103]
	v_mfma_f32_16x16x32_bf16 v[96:99], v[214:217], v[230:233], v[96:99]
	v_mfma_f32_16x16x32_bf16 v[84:87], v[192:195], v[238:241], v[84:87]
	v_mfma_f32_16x16x32_bf16 v[80:83], v[214:217], v[238:241], v[80:83]
	v_mfma_f32_16x16x32_bf16 v[68:71], v[192:195], v[246:249], v[68:71]
	v_mfma_f32_16x16x32_bf16 v[64:67], v[214:217], v[246:249], v[64:67]
	s_setprio 0
	s_barrier
; #define PG8_STAGE(bufoff, gbase, voff) do { _Pragma("unroll") for (int _i = 0; _i < 2; ++_i) \
;         __builtin_amdgcn_global_load_lds((const unsigned*)((const char*)(gbase) + (voff)[_i]), (PG8_LAS unsigned*)(lds + (bufoff) + ldsw + _i * 8192), 16, 0, 0); } while (0)
; #define PG8_LDA(dst, b, h) do { _Pragma("unroll") for (int m = 0; m < 4; ++m) _Pragma("unroll") for (int k = 0; k < 2; ++k) dst[m][k] = *(const PG8_LAS bf16x8*)(lds + PG8_SA(b, h) + aoff + m * 2048 + k * 1024); } while (0)
; #define PG8_MMA(ai, bj, At, Bt) do { __builtin_amdgcn_s_setprio(1); _Pragma("unroll") for (int m = 0; m < 4; ++m) _Pragma("unroll") for (int n = 0; n < 2; ++n) _Pragma("unroll") for (int k = 0; k < 2; ++k) \
;         acc[ai][bj][m][n] = __builtin_amdgcn_mfma_f32_16x16x32_bf16(Bt[n][k], At[m][k], acc[ai][bj][m][n], 0, 0, 0); __builtin_amdgcn_s_setprio(0); } while (0)
; #define PG8_WAIT_V(n) asm volatile("s_waitcnt vmcnt(" #n ")" ::: "memory")
; #define PG8_WAIT_L(n) asm volatile("s_waitcnt lgkmcnt(" #n ")" ::: "memory")
; #define PG8_BAR __builtin_amdgcn_s_barrier()
; #define PG8_SCHED __builtin_amdgcn_sched_barrier(0)
; template <class Epi, class Sched, bool ALIGN_EPI = false, bool SP2 = false>
; __device__ __forceinline__ void gemm_phase(PG8_LAS unsigned char* lds, const Gemm g, const Sched& S, const Epi& E, const int tid) {
;     ...
;         for (int t = 0; t < nt; t += 2) {
;     ...
;             PG8_LDA(At, 1, 1); PG8_STAGE(PG8_SB(1, 0), b3, voffB); PG8_STAGE(PG8_SB(1, 1), b3 + hstep, voffB); PG8_STAGE(PG8_SA(1, 0), a3, voffA);
;             PG8_WAIT_V(8); PG8_WAIT_L(0); PG8_BAR; PG8_MMA(1, 0, At, B0); PG8_MMA(1, 1, At, B1); PG8_BAR; PG8_SCHED;
	s_add_i32 s48, s90, s65
	v_lshl_add_u64 v[156:157], v[156:157], 0, s[28:29]
	s_mov_b32 m0, s48
	ds_read_b128 v[218:221], v175 offset:49152
	ds_read_b128 v[222:225], v175 offset:50176
	ds_read_b128 v[226:229], v175 offset:51200
	ds_read_b128 v[230:233], v175 offset:52224
	ds_read_b128 v[234:237], v175 offset:53248
	ds_read_b128 v[238:241], v175 offset:54272
	ds_read_b128 v[242:245], v175 offset:55296
	ds_read_b128 v[246:249], v175 offset:56320
	global_load_lds_dwordx4 v[156:157], off
	v_lshl_add_u64 v[156:157], v[250:251], 0, s[28:29]
	s_add_i32 m0, s48, 0x2000
	s_add_i32 s48, s91, s65
	global_load_lds_dwordx4 v[156:157], off
	v_lshl_add_u64 v[156:157], v[178:179], 0, s[28:29]
	s_mov_b32 m0, s48
	s_nop 0
	global_load_lds_dwordx4 v[156:157], off
	v_lshl_add_u64 v[156:157], v[180:181], 0, s[28:29]
	s_add_i32 m0, s48, 0x2000
	s_nop 0
	global_load_lds_dwordx4 v[156:157], off
	v_lshl_add_u64 v[156:157], v[204:205], 0, s[28:29]
	s_mov_b32 m0, s70
	s_nop 0
	global_load_lds_dwordx4 v[156:157], off
	v_lshl_add_u64 v[156:157], v[196:197], 0, s[28:29]
	s_mov_b32 m0, s71
	s_nop 0
	global_load_lds_dwordx4 v[156:157], off
	s_waitcnt vmcnt(8)
	s_waitcnt lgkmcnt(0)
	s_barrier
	s_setprio 1
	s_waitcnt lgkmcnt(0)
	v_mfma_f32_16x16x32_bf16 v[60:63], v[144:147], v[218:221], v[60:63]
	v_mfma_f32_16x16x32_bf16 v[56:59], v[152:155], v[218:221], v[56:59]
	v_mfma_f32_16x16x32_bf16 v[44:47], v[144:147], v[226:229], v[44:47]
	v_mfma_f32_16x16x32_bf16 v[40:43], v[152:155], v[226:229], v[40:43]
	v_mfma_f32_16x16x32_bf16 v[28:31], v[144:147], v[234:237], v[28:31]
	v_mfma_f32_16x16x32_bf16 v[24:27], v[152:155], v[234:237], v[24:27]
	v_mfma_f32_16x16x32_bf16 v[12:15], v[144:147], v[242:245], v[12:15]
	v_mfma_f32_16x16x32_bf16 v[8:11], v[152:155], v[242:245], v[8:11]
	v_mfma_f32_16x16x32_bf16 v[60:63], v[148:151], v[222:225], v[60:63]
	v_mfma_f32_16x16x32_bf16 v[56:59], v[184:187], v[222:225], v[56:59]
	v_mfma_f32_16x16x32_bf16 v[44:47], v[148:151], v[230:233], v[44:47]
	v_mfma_f32_16x16x32_bf16 v[40:43], v[184:187], v[230:233], v[40:43]
	v_mfma_f32_16x16x32_bf16 v[28:31], v[148:151], v[238:241], v[28:31]
	v_mfma_f32_16x16x32_bf16 v[24:27], v[184:187], v[238:241], v[24:27]
	v_mfma_f32_16x16x32_bf16 v[12:15], v[148:151], v[246:249], v[12:15]
	v_mfma_f32_16x16x32_bf16 v[8:11], v[184:187], v[246:249], v[8:11]
	s_setprio 0
	s_setprio 1
	v_mfma_f32_16x16x32_bf16 v[52:55], v[188:191], v[218:221], v[52:55]
	v_mfma_f32_16x16x32_bf16 v[48:51], v[208:211], v[218:221], v[48:51]
	v_mfma_f32_16x16x32_bf16 v[36:39], v[188:191], v[226:229], v[36:39]
	v_mfma_f32_16x16x32_bf16 v[32:35], v[208:211], v[226:229], v[32:35]
	v_mfma_f32_16x16x32_bf16 v[20:23], v[188:191], v[234:237], v[20:23]
	v_mfma_f32_16x16x32_bf16 v[16:19], v[208:211], v[234:237], v[16:19]
	v_mfma_f32_16x16x32_bf16 v[4:7], v[188:191], v[242:245], v[4:7]
	v_mfma_f32_16x16x32_bf16 v[0:3], v[208:211], v[242:245], v[0:3]
	v_mfma_f32_16x16x32_bf16 v[52:55], v[192:195], v[222:225], v[52:55]
	v_mfma_f32_16x16x32_bf16 v[48:51], v[214:217], v[222:225], v[48:51]
	v_mfma_f32_16x16x32_bf16 v[36:39], v[192:195], v[230:233], v[36:39]
	v_mfma_f32_16x16x32_bf16 v[32:35], v[214:217], v[230:233], v[32:35]
	v_mfma_f32_16x16x32_bf16 v[20:23], v[192:195], v[238:241], v[20:23]
	v_mfma_f32_16x16x32_bf16 v[16:19], v[214:217], v[238:241], v[16:19]
	v_mfma_f32_16x16x32_bf16 v[4:7], v[192:195], v[246:249], v[4:7]
	v_mfma_f32_16x16x32_bf16 v[0:3], v[214:217], v[246:249], v[0:3]
	s_setprio 0
	s_barrier
	s_add_u32 s44, s44, 0x100
	s_addc_u32 s45, s45, 0
	s_add_u32 s37, s37, 0x100
	s_addc_u32 s50, s50, 0
	s_cmp_ge_u32 s51, s80
	s_mov_b32 s48, s51
	s_cbranch_scc1 .Lmy_kdone_3

; #define PG8_BAR __builtin_amdgcn_s_barrier()
; template <class Epi, class Sched, bool ALIGN_EPI = false, bool SP2 = false>
; __device__ __forceinline__ void gemm_phase(PG8_LAS unsigned char* lds, const Gemm g, const Sched& S, const Epi& E, const int tid) {
;     ...
;         if constexpr (ALIGN_EPI) { if (wr == 0) PG8_BAR; }
.Lmy_kdone_3:
	s_and_b64 vcc, exec, s[26:27]
	s_cbranch_vccz .LBB0_624
	s_barrier
